# GEMM K-loops: one static s_setprio 1 for the younger co-resident workgroup (blockIdx >= 256) around the MFMA mainloop, reset after
# speedup vs baseline: 1.0255x; 1.0192x over previous
.LBB0_60:
	s_mov_b64 s[6:7], -1
	s_and_b64 vcc, exec, s[4:5]
	s_cbranch_vccz .LBB0_52
	v_mov_b32_e32 v71, v139
	v_readlane_b32 s52, v246, 25
	v_ashrrev_i32_e32 v68, 6, v71
	s_waitcnt vmcnt(48)
	v_lshlrev_b32_e32 v6, 3, v68
	v_bfe_u32 v70, v71, 3, 3
	v_or_b32_e32 v2, v6, v70
	v_lshrrev_b32_e32 v7, 1, v2
	s_lshl_b32 s5, s9, 7
	v_xor_b32_e32 v3, v7, v71
	v_readlane_b32 s54, v246, 27
	v_readlane_b32 s55, v246, 28
	v_readlane_b32 s36, v246, 9
	s_lshl_b32 s4, s10, 7
	v_add_u32_e32 v4, s5, v2
	v_mov_b64_e32 v[0:1], s[54:55]
	s_movk_i32 s9, 0x2080
	v_lshlrev_b32_e32 v3, 4, v3
	v_readlane_b32 s38, v246, 11
	v_readlane_b32 s39, v246, 12
	v_mad_i64_i32 v[0:1], s[6:7], v4, s9, v[0:1]
	v_and_b32_e32 v136, 0x70, v3
	v_add_u32_e32 v4, s4, v2
	v_mov_b64_e32 v[2:3], s[38:39]
	v_mad_i64_i32 v[2:3], s[6:7], v4, s9, v[2:3]
	v_lshlrev_b32_e32 v72, 10, v68
	v_add_u32_e32 v4, 0x4000, v72
	v_readfirstlane_b32 s6, v72
	v_lshl_add_u64 v[0:1], v[0:1], 0, v[136:137]
	s_mov_b32 m0, s6
	v_readfirstlane_b32 s6, v4
	v_add_u32_e32 v9, 0x1000, v72
	v_lshl_add_u64 v[2:3], v[2:3], 0, v[136:137]
	global_load_lds_dwordx4 v[0:1], off
	s_mov_b32 m0, s6
	s_mov_b64 s[10:11], 0x41000
	v_readfirstlane_b32 s6, v9
	v_add_u32_e32 v9, 0x5000, v72
	global_load_lds_dwordx4 v[2:3], off
	v_lshl_add_u64 v[4:5], v[0:1], 0, s[10:11]
	s_mov_b32 m0, s6
	v_readfirstlane_b32 s6, v9
	v_add_u32_e32 v9, 0x2000, v72
	global_load_lds_dwordx4 v[4:5], off
	v_lshl_add_u64 v[4:5], v[2:3], 0, s[10:11]
	s_mov_b32 m0, s6
	s_mov_b64 s[10:11], 0x82000
	v_readfirstlane_b32 s6, v9
	v_add_u32_e32 v9, 0x6000, v72
	global_load_lds_dwordx4 v[4:5], off
	v_lshl_add_u64 v[4:5], v[0:1], 0, s[10:11]
	s_mov_b32 m0, s6
	v_readfirstlane_b32 s6, v9
	global_load_lds_dwordx4 v[4:5], off
	v_lshl_add_u64 v[4:5], v[2:3], 0, s[10:11]
	s_mov_b32 m0, s6
	s_mov_b64 s[10:11], 0xc3000
	global_load_lds_dwordx4 v[4:5], off
	v_add_u32_e32 v4, 0x3000, v72
	v_lshl_add_u64 v[0:1], v[0:1], 0, s[10:11]
	v_readfirstlane_b32 s6, v4
	s_mov_b32 m0, s6
	v_bfe_u32 v75, v71, 4, 2
	global_load_lds_dwordx4 v[0:1], off
	v_lshl_add_u64 v[0:1], v[2:3], 0, s[10:11]
	v_add_u32_e32 v2, 0x7000, v72
	v_and_b32_e32 v76, 15, v71
	v_readfirstlane_b32 s6, v2
	s_mov_b32 m0, s6
	v_lshrrev_b32_e32 v8, 1, v71
	global_load_lds_dwordx4 v[0:1], off
	v_ashrrev_i32_e32 v1, 1, v71
	v_bfe_u32 v0, v71, 1, 3
	v_and_b32_e32 v69, 0xffffffc0, v1
	v_or_b32_e32 v1, v69, v76
	v_bitop3_b32 v0, v75, v0, 4 bitop3:0x36
	v_lshlrev_b32_e32 v73, 7, v1
	v_bitop3_b32 v1, v75, v8, 7 bitop3:0x78
	v_lshlrev_b32_e32 v77, 4, v0
	v_or_b32_e32 v0, s5, v70
	v_lshlrev_b32_e32 v78, 4, v1
	v_lshlrev_b32_e32 v1, 7, v71
	v_add_u32_e32 v0, v0, v6
	v_bitop3_b32 v2, v7, 7, v71 bitop3:0x48
	v_and_b32_e32 v74, 0x2780, v1
	v_mad_i64_i32 v[0:1], s[6:7], v0, s9, 0
	v_lshlrev_b32_e32 v2, 4, v2
	v_or_b32_e32 v0, v0, v2
	v_lshl_add_u64 v[64:65], s[54:55], 0, v[0:1]
	v_or_b32_e32 v0, s4, v70
	v_add_u32_e32 v0, v0, v6
	v_mad_i64_i32 v[0:1], s[6:7], v0, s9, 0
	s_waitcnt vmcnt(0)
	v_or_b32_e32 v0, v0, v2
	v_lshl_add_u64 v[66:67], s[38:39], 0, v[0:1]
	v_mov_b32_e32 v0, 0
	s_mov_b64 s[6:7], 0
	s_mov_b32 s9, 0
	v_mov_b32_e32 v1, v0
	v_mov_b32_e32 v2, v0
	v_mov_b32_e32 v3, v0
	v_mov_b32_e32 v4, v0
	v_mov_b32_e32 v5, v0
	v_mov_b32_e32 v6, v0
	v_mov_b32_e32 v7, v0
	v_mov_b32_e32 v8, v0
	v_mov_b32_e32 v9, v0
	v_mov_b32_e32 v10, v0
	v_mov_b32_e32 v11, v0
	s_waitcnt vmcnt(0)
	v_mov_b32_e32 v12, v0
	v_mov_b32_e32 v13, v0
	v_mov_b32_e32 v14, v0
	v_mov_b32_e32 v15, v0
	v_mov_b32_e32 v16, v0
	v_mov_b32_e32 v17, v0
	v_mov_b32_e32 v18, v0
	v_mov_b32_e32 v19, v0
	v_mov_b32_e32 v20, v0
	v_mov_b32_e32 v21, v0
	v_mov_b32_e32 v22, v0
	v_mov_b32_e32 v23, v0
	v_mov_b32_e32 v24, v0
	v_mov_b32_e32 v25, v0
	v_mov_b32_e32 v26, v0
	v_mov_b32_e32 v27, v0
	v_mov_b32_e32 v28, v0
	v_mov_b32_e32 v29, v0
	v_mov_b32_e32 v30, v0
	v_mov_b32_e32 v31, v0
	v_mov_b32_e32 v32, v0
	v_mov_b32_e32 v33, v0
	v_mov_b32_e32 v34, v0
	v_mov_b32_e32 v35, v0
	v_mov_b32_e32 v36, v0
	v_mov_b32_e32 v37, v0
	v_mov_b32_e32 v38, v0
	v_mov_b32_e32 v39, v0
	v_mov_b32_e32 v40, v0
	v_mov_b32_e32 v41, v0
	v_mov_b32_e32 v42, v0
	v_mov_b32_e32 v43, v0
	v_mov_b32_e32 v44, v0
	v_mov_b32_e32 v45, v0
	v_mov_b32_e32 v46, v0
	v_mov_b32_e32 v47, v0
	v_mov_b32_e32 v48, v0
	v_mov_b32_e32 v49, v0
	v_mov_b32_e32 v50, v0
	v_mov_b32_e32 v51, v0
	v_mov_b32_e32 v52, v0
	v_mov_b32_e32 v53, v0
	v_mov_b32_e32 v54, v0
	v_mov_b32_e32 v55, v0
	v_mov_b32_e32 v56, v0
	v_mov_b32_e32 v57, v0
	v_mov_b32_e32 v58, v0
	v_mov_b32_e32 v59, v0
	v_mov_b32_e32 v60, v0
	v_mov_b32_e32 v61, v0
	v_mov_b32_e32 v62, v0
	v_mov_b32_e32 v63, v0
	s_mov_b64 s[12:13], 0x41080
	s_mov_b64 s[14:15], 0x82080
	s_mov_b64 s[16:17], 0xc3080
	v_readlane_b32 s53, v246, 26
	v_readlane_b32 s56, v246, 29
	v_readlane_b32 s57, v246, 30
	v_readlane_b32 s58, v246, 31
	v_readlane_b32 s59, v246, 32
	v_readlane_b32 s60, v246, 33
	v_readlane_b32 s61, v246, 34
	v_readlane_b32 s62, v246, 35
	v_readlane_b32 s63, v246, 36
	v_readlane_b32 s64, v246, 37
	v_readlane_b32 s65, v246, 38
	v_readlane_b32 s66, v246, 39
	v_readlane_b32 s67, v246, 40
	v_readlane_b32 s37, v246, 10
	v_readlane_b32 s40, v246, 13
	v_readlane_b32 s41, v246, 14
	v_readlane_b32 s42, v246, 15
	v_readlane_b32 s43, v246, 16
	v_readlane_b32 s44, v246, 17
	v_readlane_b32 s45, v246, 18
	v_readlane_b32 s46, v246, 19
	v_readlane_b32 s47, v246, 20
	v_readlane_b32 s48, v246, 21
	v_readlane_b32 s49, v246, 22
	v_readlane_b32 s50, v246, 23
	v_readlane_b32 s51, v246, 24
	s_waitcnt vmcnt(0) lgkmcnt(0)
	s_barrier
	s_bitcmp1_b32 s68, 8
	s_cbranch_scc0 gp62_skip
	s_setprio 1
gp62_skip:
.LBB0_62:
	s_and_b32 s10, s9, 0x8000
	s_xor_b32 s11, s10, 0x8000
	v_add_u32_e32 v79, s11, v72
	v_lshl_add_u64 v[80:81], v[64:65], 0, s[6:7]
	v_readfirstlane_b32 s11, v79
	v_lshl_add_u64 v[82:83], v[80:81], 0, s[28:29]
	s_mov_b32 m0, s11
	v_lshl_add_u64 v[84:85], v[66:67], 0, s[6:7]
	global_load_lds_dwordx4 v[82:83], off
	v_add_u32_e32 v82, 0x4000, v79
	v_lshl_add_u64 v[86:87], v[84:85], 0, s[28:29]
	v_readfirstlane_b32 s11, v82
	s_mov_b32 m0, s11
	v_lshl_add_u64 v[82:83], v[80:81], 0, s[12:13]
	global_load_lds_dwordx4 v[86:87], off
	v_add_u32_e32 v86, 0x1000, v79
	s_nop 0
	v_readfirstlane_b32 s11, v86
	v_add_u32_e32 v86, 0x5000, v79
	s_mov_b32 m0, s11
	v_readfirstlane_b32 s11, v86
	v_add_u32_e32 v86, 0x2000, v79
	global_load_lds_dwordx4 v[82:83], off
	v_lshl_add_u64 v[82:83], v[84:85], 0, s[12:13]
	s_mov_b32 m0, s11
	v_readfirstlane_b32 s11, v86
	v_add_u32_e32 v86, 0x6000, v79
	global_load_lds_dwordx4 v[82:83], off
	v_lshl_add_u64 v[82:83], v[80:81], 0, s[14:15]
	s_mov_b32 m0, s11
	v_readfirstlane_b32 s11, v86
	global_load_lds_dwordx4 v[82:83], off
	v_lshl_add_u64 v[82:83], v[84:85], 0, s[14:15]
	s_mov_b32 m0, s11
	v_lshl_add_u64 v[80:81], v[80:81], 0, s[16:17]
	global_load_lds_dwordx4 v[82:83], off
	v_add_u32_e32 v82, 0x3000, v79
	v_add_u32_e32 v79, 0x7000, v79
	v_readfirstlane_b32 s11, v82
	s_mov_b32 m0, s11
	v_readfirstlane_b32 s11, v79
	global_load_lds_dwordx4 v[80:81], off
	v_lshl_add_u64 v[80:81], v[84:85], 0, s[16:17]
	s_mov_b32 m0, s11
	v_or_b32_e32 v79, s10, v78
	global_load_lds_dwordx4 v[80:81], off
	v_add_u32_e32 v100, v79, v73
	v_add_u32_e32 v79, v79, v74
	ds_read_b128 v[80:83], v100
	ds_read_b128 v[84:87], v100 offset:2048
	ds_read_b128 v[88:91], v79 offset:16384
	ds_read_b128 v[92:95], v79 offset:18432
	ds_read_b128 v[96:99], v100 offset:4096
	ds_read_b128 v[100:103], v100 offset:6144
	ds_read_b128 v[104:107], v79 offset:20480
	ds_read_b128 v[108:111], v79 offset:22528
	v_or_b32_e32 v79, s10, v77
	v_add_u32_e32 v132, v79, v73
	v_add_u32_e32 v79, v79, v74
	ds_read_b128 v[112:115], v132
	ds_read_b128 v[116:119], v132 offset:2048
	ds_read_b128 v[120:123], v79 offset:16384
	ds_read_b128 v[124:127], v79 offset:18432
	ds_read_b128 v[128:131], v132 offset:4096
	ds_read_b128 v[132:135], v132 offset:6144
	ds_read_b128 v[146:149], v79 offset:20480
	ds_read_b128 v[150:153], v79 offset:22528
	s_waitcnt lgkmcnt(0)
	v_mfma_f32_16x16x32_bf16 v[60:63], v[80:83], v[88:91], v[60:63]
	v_mfma_f32_16x16x32_bf16 v[56:59], v[80:83], v[92:95], v[56:59]
	v_mfma_f32_16x16x32_bf16 v[52:55], v[80:83], v[104:107], v[52:55]
	v_mfma_f32_16x16x32_bf16 v[48:51], v[80:83], v[108:111], v[48:51]
	v_mfma_f32_16x16x32_bf16 v[44:47], v[84:87], v[88:91], v[44:47]
	v_mfma_f32_16x16x32_bf16 v[40:43], v[84:87], v[92:95], v[40:43]
	v_mfma_f32_16x16x32_bf16 v[36:39], v[84:87], v[104:107], v[36:39]
	v_mfma_f32_16x16x32_bf16 v[32:35], v[84:87], v[108:111], v[32:35]
	v_mfma_f32_16x16x32_bf16 v[28:31], v[96:99], v[88:91], v[28:31]
	v_mfma_f32_16x16x32_bf16 v[24:27], v[96:99], v[92:95], v[24:27]
	v_mfma_f32_16x16x32_bf16 v[20:23], v[96:99], v[104:107], v[20:23]
	v_mfma_f32_16x16x32_bf16 v[16:19], v[96:99], v[108:111], v[16:19]
	v_mfma_f32_16x16x32_bf16 v[12:15], v[100:103], v[88:91], v[12:15]
	v_mfma_f32_16x16x32_bf16 v[8:11], v[100:103], v[92:95], v[8:11]
	v_mfma_f32_16x16x32_bf16 v[4:7], v[100:103], v[104:107], v[4:7]
	v_mfma_f32_16x16x32_bf16 v[0:3], v[100:103], v[108:111], v[0:3]
	v_mfma_f32_16x16x32_bf16 v[60:63], v[112:115], v[120:123], v[60:63]
	v_mfma_f32_16x16x32_bf16 v[56:59], v[112:115], v[124:127], v[56:59]
	v_mfma_f32_16x16x32_bf16 v[52:55], v[112:115], v[146:149], v[52:55]
	v_mfma_f32_16x16x32_bf16 v[48:51], v[112:115], v[150:153], v[48:51]
	v_mfma_f32_16x16x32_bf16 v[44:47], v[116:119], v[120:123], v[44:47]
	v_mfma_f32_16x16x32_bf16 v[40:43], v[116:119], v[124:127], v[40:43]
	v_mfma_f32_16x16x32_bf16 v[36:39], v[116:119], v[146:149], v[36:39]
	v_mfma_f32_16x16x32_bf16 v[32:35], v[116:119], v[150:153], v[32:35]
	v_mfma_f32_16x16x32_bf16 v[28:31], v[128:131], v[120:123], v[28:31]
	v_mfma_f32_16x16x32_bf16 v[24:27], v[128:131], v[124:127], v[24:27]
	v_mfma_f32_16x16x32_bf16 v[20:23], v[128:131], v[146:149], v[20:23]
	v_mfma_f32_16x16x32_bf16 v[16:19], v[128:131], v[150:153], v[16:19]
	v_mfma_f32_16x16x32_bf16 v[12:15], v[132:135], v[120:123], v[12:15]
	v_mfma_f32_16x16x32_bf16 v[8:11], v[132:135], v[124:127], v[8:11]
	v_mfma_f32_16x16x32_bf16 v[4:7], v[132:135], v[146:149], v[4:7]
	v_mfma_f32_16x16x32_bf16 v[0:3], v[132:135], v[150:153], v[0:3]
	s_waitcnt vmcnt(0)
	s_add_u32 s6, s6, 0x80
	s_addc_u32 s7, s7, 0
	s_add_i32 s9, s9, 0x8000
	s_cmpk_eq_i32 s6, 0x1f80
	s_barrier
	s_cbranch_scc0 .LBB0_62
	s_setprio 0
	v_add_u32_e32 v72, v78, v73
	v_add_u32_e32 v102, v78, v74
	ds_read_b128 v[64:67], v72 offset:32768
	ds_read_b128 v[78:81], v72 offset:34816
	ds_read_b128 v[82:85], v102 offset:49152
	ds_read_b128 v[86:89], v102 offset:51200
	ds_read_b128 v[90:93], v72 offset:36864
	ds_read_b128 v[94:97], v72 offset:38912
	ds_read_b128 v[98:101], v102 offset:53248
	ds_read_b128 v[102:105], v102 offset:55296
	v_add_u32_e32 v72, v77, v73
	v_add_u32_e32 v73, v77, v74
	ds_read_b128 v[106:109], v72 offset:32768
	ds_read_b128 v[110:113], v72 offset:34816
	ds_read_b128 v[114:117], v73 offset:49152
	ds_read_b128 v[118:121], v73 offset:51200
	ds_read_b128 v[122:125], v72 offset:36864
	ds_read_b128 v[126:129], v72 offset:38912
	ds_read_b128 v[130:133], v73 offset:53248
	ds_read_b128 v[146:149], v73 offset:55296
	s_waitcnt lgkmcnt(13)
	v_mfma_f32_16x16x32_bf16 v[60:63], v[64:67], v[82:85], v[60:63]
	s_waitcnt lgkmcnt(12)
	v_mfma_f32_16x16x32_bf16 v[56:59], v[64:67], v[86:89], v[56:59]
	s_waitcnt lgkmcnt(9)
	v_mfma_f32_16x16x32_bf16 v[52:55], v[64:67], v[98:101], v[52:55]
	s_waitcnt lgkmcnt(8)
	v_mfma_f32_16x16x32_bf16 v[48:51], v[64:67], v[102:105], v[48:51]
	v_mfma_f32_16x16x32_bf16 v[44:47], v[78:81], v[82:85], v[44:47]
	v_mfma_f32_16x16x32_bf16 v[40:43], v[78:81], v[86:89], v[40:43]
	v_mfma_f32_16x16x32_bf16 v[36:39], v[78:81], v[98:101], v[36:39]
	v_mfma_f32_16x16x32_bf16 v[32:35], v[78:81], v[102:105], v[32:35]
	v_mfma_f32_16x16x32_bf16 v[28:31], v[90:93], v[82:85], v[28:31]
	v_mfma_f32_16x16x32_bf16 v[24:27], v[90:93], v[86:89], v[24:27]
	v_mfma_f32_16x16x32_bf16 v[20:23], v[90:93], v[98:101], v[20:23]
	v_mfma_f32_16x16x32_bf16 v[16:19], v[90:93], v[102:105], v[16:19]
	v_mfma_f32_16x16x32_bf16 v[12:15], v[94:97], v[82:85], v[12:15]
	v_mfma_f32_16x16x32_bf16 v[8:11], v[94:97], v[86:89], v[8:11]
	v_mfma_f32_16x16x32_bf16 v[4:7], v[94:97], v[98:101], v[4:7]
	v_mfma_f32_16x16x32_bf16 v[0:3], v[94:97], v[102:105], v[0:3]
	s_waitcnt lgkmcnt(5)
	v_mfma_f32_16x16x32_bf16 v[78:81], v[106:109], v[114:117], v[60:63]
	s_waitcnt lgkmcnt(4)
	v_mfma_f32_16x16x32_bf16 v[56:59], v[106:109], v[118:121], v[56:59]
	s_waitcnt lgkmcnt(1)
	v_mfma_f32_16x16x32_bf16 v[52:55], v[106:109], v[130:133], v[52:55]
	s_waitcnt lgkmcnt(0)
	v_mfma_f32_16x16x32_bf16 v[48:51], v[106:109], v[146:149], v[48:51]
	v_mfma_f32_16x16x32_bf16 v[44:47], v[110:113], v[114:117], v[44:47]
	v_mfma_f32_16x16x32_bf16 v[40:43], v[110:113], v[118:121], v[40:43]
	v_mfma_f32_16x16x32_bf16 v[36:39], v[110:113], v[130:133], v[36:39]
	v_mfma_f32_16x16x32_bf16 v[32:35], v[110:113], v[146:149], v[32:35]
	v_mfma_f32_16x16x32_bf16 v[28:31], v[122:125], v[114:117], v[28:31]
	v_mfma_f32_16x16x32_bf16 v[24:27], v[122:125], v[118:121], v[24:27]
	v_mfma_f32_16x16x32_bf16 v[20:23], v[122:125], v[130:133], v[20:23]
	v_mfma_f32_16x16x32_bf16 v[16:19], v[122:125], v[146:149], v[16:19]
	v_mfma_f32_16x16x32_bf16 v[12:15], v[126:129], v[114:117], v[12:15]
	v_mfma_f32_16x16x32_bf16 v[8:11], v[126:129], v[118:121], v[8:11]
	v_mfma_f32_16x16x32_bf16 v[4:7], v[126:129], v[130:133], v[4:7]
	v_mfma_f32_16x16x32_bf16 v[0:3], v[126:129], v[146:149], v[0:3]
	v_add_u32_e32 v72, s5, v69
	v_add_u32_e32 v61, 0xfffff000, v72
	s_movk_i32 s6, 0x2400
	v_lshl_or_b32 v60, v75, 2, v72
	v_lshrrev_b32_e32 v61, 12, v61
	s_movk_i32 s9, 0xfff
	v_mul_lo_u32 v74, v68, s6
	v_add_u32_e32 v61, 1, v61
	v_cmp_lt_i32_e32 vcc, s9, v60
	v_readlane_b32 s6, v245, 34
	v_readlane_b32 s7, v245, 35
	v_cndmask_b32_e32 v136, 0, v61, vcc
	v_lshl_add_u64 v[66:67], v[136:137], 0, s[0:1]
	v_mov_b64_e32 v[64:65], s[6:7]
	s_movk_i32 s5, 0x6000
	v_mad_u64_u32 v[68:69], s[6:7], v66, s5, v[64:65]
	v_or_b32_e32 v66, 1, v60
	v_mad_i32_i24 v69, v67, s5, v69
	v_ashrrev_i32_e32 v67, 31, v66
	v_lshlrev_b64 v[84:85], 12, v[66:67]
	v_or_b32_e32 v66, 2, v60
	v_and_b32_e32 v73, 64, v71
	v_ashrrev_i32_e32 v67, 31, v66
	v_or3_b32 v62, v76, s4, v73
	v_lshlrev_b64 v[86:87], 12, v[66:67]
	v_or_b32_e32 v66, 3, v60
	v_readlane_b32 s36, v247, 57
	v_ashrrev_i32_e32 v61, 31, v60
	v_ashrrev_i32_e32 v67, 31, v66
	v_ashrrev_i32_e32 v63, 31, v62
	v_readlane_b32 s46, v246, 3
	v_readlane_b32 s47, v246, 4
	v_lshlrev_b64 v[82:83], 12, v[60:61]
	v_lshlrev_b64 v[88:89], 12, v[66:67]
	v_lshlrev_b64 v[66:67], 2, v[62:63]
	v_lshl_add_u64 v[62:63], v[62:63], 1, s[46:47]
	v_lshl_add_u64 v[82:83], v[62:63], 0, v[82:83]
	s_waitcnt vmcnt(0)
	s_barrier
	global_load_ushort v202, v[82:83], off
	v_lshl_add_u64 v[68:69], v[68:69], 0, v[66:67]
	global_load_dword v203, v[68:69], off
	v_lshl_add_u64 v[84:85], v[62:63], 0, v[84:85]
	global_load_ushort v204, v[84:85], off
	s_movk_i32 s6, 0x240
	s_movk_i32 s36, 0x880
	v_readlane_b32 s37, v247, 58
	v_readlane_b32 s38, v247, 59
	v_readlane_b32 s39, v247, 60
	v_readlane_b32 s40, v247, 61
	v_readlane_b32 s41, v247, 62
	v_readlane_b32 s42, v247, 63
	v_readlane_b32 s43, v246, 0
	v_readlane_b32 s44, v246, 1
	v_readlane_b32 s45, v246, 2
	v_readlane_b32 s48, v246, 5
	v_readlane_b32 s49, v246, 6
	v_readlane_b32 s50, v246, 7
	v_readlane_b32 s51, v246, 8
	s_waitcnt vmcnt(2)
	v_lshlrev_b32_e32 v77, 16, v202
	v_mul_f32_e32 v77, 0x3fd744fd, v77
	s_waitcnt vmcnt(1)
	v_fmac_f32_e32 v77, v78, v203
	s_waitcnt vmcnt(0)
	v_lshlrev_b32_e32 v78, 16, v204
	v_mul_f32_e32 v90, 0x3fd744fd, v78
	v_fmac_f32_e32 v90, v79, v203
	v_lshl_add_u64 v[78:79], v[62:63], 0, v[86:87]
	global_load_ushort v205, v[78:79], off
	s_waitcnt vmcnt(0)
	v_lshlrev_b32_e32 v86, 16, v205
	v_mul_f32_e32 v91, 0x3fd744fd, v86
	v_lshl_add_u64 v[86:87], v[62:63], 0, v[88:89]
	global_load_ushort v206, v[86:87], off
	global_load_dword v207, v[68:69], off offset:64
	global_load_ushort v208, v[82:83], off offset:32
	global_load_ushort v209, v[84:85], off offset:32
	global_load_ushort v210, v[78:79], off offset:32
	global_load_ushort v211, v[86:87], off offset:32
	global_load_dword v212, v[68:69], off offset:128
	global_load_ushort v213, v[82:83], off offset:64
	global_load_ushort v214, v[84:85], off offset:64
	global_load_ushort v215, v[78:79], off offset:64
	global_load_ushort v216, v[86:87], off offset:64
	global_load_dword v217, v[68:69], off offset:192
	global_load_ushort v218, v[82:83], off offset:96
	global_load_ushort v219, v[84:85], off offset:96
	global_load_ushort v220, v[78:79], off offset:96
	global_load_ushort v221, v[86:87], off offset:96
	v_fmac_f32_e32 v91, v80, v203
	s_waitcnt vmcnt(15)
	v_lshlrev_b32_e32 v80, 16, v206
	v_mul_f32_e32 v80, 0x3fd744fd, v80
	v_fmac_f32_e32 v80, v81, v203
	v_lshl_or_b32 v61, v76, 1, v74
	v_mad_u32_u24 v61, v75, s6, v61
	v_cvt_pk_bf16_f32 v75, v90, s0
	ds_write_b16 v61, v75 offset:144
	v_cvt_pk_bf16_f32 v75, v91, s0
	v_cvt_pk_bf16_f32 v76, v77, s0
	ds_write_b16 v61, v75 offset:288
	v_cvt_pk_bf16_f32 v75, v80, s0
	ds_write_b16 v61, v76
	ds_write_b16 v61, v75 offset:432
	s_waitcnt vmcnt(13)
	v_lshlrev_b32_e32 v76, 16, v208
	v_mul_f32_e32 v76, 0x3fd744fd, v76
	v_fmac_f32_e32 v76, v56, v207
	s_waitcnt vmcnt(12)
	v_lshlrev_b32_e32 v56, 16, v209
	v_mul_f32_e32 v56, 0x3fd744fd, v56
	v_fmac_f32_e32 v56, v57, v207
	v_cvt_pk_bf16_f32 v56, v56, s0
	ds_write_b16 v61, v56 offset:176
	s_waitcnt vmcnt(11)
	v_lshlrev_b32_e32 v57, 16, v210
	v_mul_f32_e32 v57, 0x3fd744fd, v57
	v_fmac_f32_e32 v57, v58, v207
	v_cvt_pk_bf16_f32 v56, v57, s0
	ds_write_b16 v61, v56 offset:320
	s_waitcnt vmcnt(10)
	v_lshlrev_b32_e32 v58, 16, v211
	v_mul_f32_e32 v58, 0x3fd744fd, v58
	v_fmac_f32_e32 v58, v59, v207
	v_cvt_pk_bf16_f32 v59, v76, s0
	v_cvt_pk_bf16_f32 v56, v58, s0
	ds_write_b16 v61, v59 offset:32
	ds_write_b16 v61, v56 offset:464
	s_waitcnt vmcnt(8)
	v_lshlrev_b32_e32 v57, 16, v213
	v_mul_f32_e32 v57, 0x3fd744fd, v57
	v_fmac_f32_e32 v57, v52, v212
	s_waitcnt vmcnt(7)
	v_lshlrev_b32_e32 v52, 16, v214
	v_mul_f32_e32 v52, 0x3fd744fd, v52
	v_fmac_f32_e32 v52, v53, v212
	v_cvt_pk_bf16_f32 v52, v52, s0
	ds_write_b16 v61, v52 offset:208
	s_waitcnt vmcnt(6)
	v_lshlrev_b32_e32 v53, 16, v215
	v_mul_f32_e32 v53, 0x3fd744fd, v53
	v_fmac_f32_e32 v53, v54, v212
	v_cvt_pk_bf16_f32 v52, v53, s0
	ds_write_b16 v61, v52 offset:352
	s_waitcnt vmcnt(5)
	v_lshlrev_b32_e32 v54, 16, v216
	v_mul_f32_e32 v54, 0x3fd744fd, v54
	v_fmac_f32_e32 v54, v55, v212
	v_cvt_pk_bf16_f32 v55, v57, s0
	v_cvt_pk_bf16_f32 v52, v54, s0
	ds_write_b16 v61, v55 offset:64
	ds_write_b16 v61, v52 offset:496
	v_or_b32_e32 v54, 18, v60
	v_ashrrev_i32_e32 v55, 31, v54
	v_lshlrev_b64 v[56:57], 12, v[54:55]
	v_or_b32_e32 v54, 19, v60
	v_ashrrev_i32_e32 v55, 31, v54
	v_lshlrev_b64 v[58:59], 12, v[54:55]
	s_waitcnt vmcnt(3)
	v_lshlrev_b32_e32 v53, 16, v218
	v_mul_f32_e32 v53, 0x3fd744fd, v53
	v_fmac_f32_e32 v53, v48, v217
	s_waitcnt vmcnt(2)
	v_lshlrev_b32_e32 v48, 16, v219
	v_mul_f32_e32 v48, 0x3fd744fd, v48
	v_fmac_f32_e32 v48, v49, v217
	v_cvt_pk_bf16_f32 v48, v48, s0
	ds_write_b16 v61, v48 offset:240
	s_waitcnt vmcnt(1)
	v_lshlrev_b32_e32 v49, 16, v220
	v_mul_f32_e32 v49, 0x3fd744fd, v49
	v_fmac_f32_e32 v49, v50, v217
	v_cvt_pk_bf16_f32 v48, v49, s0
	ds_write_b16 v61, v48 offset:384
	v_add_u32_e32 v49, 0xfffff010, v72
	v_lshrrev_b32_e32 v49, 12, v49
	v_add_u32_e32 v49, 1, v49
	s_waitcnt vmcnt(0)
	v_lshlrev_b32_e32 v50, 16, v221
	v_mul_f32_e32 v50, 0x3fd744fd, v50
	v_fmac_f32_e32 v50, v51, v217
	v_cvt_pk_bf16_f32 v48, v50, s0
	ds_write_b16 v61, v48 offset:528
	v_or_b32_e32 v48, 16, v60
	v_cmp_lt_i32_e32 vcc, s9, v48
	v_cvt_pk_bf16_f32 v51, v53, s0
	ds_write_b16 v61, v51 offset:96
	v_cndmask_b32_e32 v136, 0, v49, vcc
	v_ashrrev_i32_e32 v49, 31, v48
	v_lshl_add_u64 v[50:51], v[136:137], 0, s[0:1]
	v_lshlrev_b64 v[48:49], 12, v[48:49]
	v_mad_u64_u32 v[52:53], s[6:7], v50, s5, v[64:65]
	v_lshl_add_u64 v[54:55], v[62:63], 0, v[48:49]
	global_load_ushort v222, v[54:55], off
	v_mad_i32_i24 v53, v51, s5, v53
	v_lshl_add_u64 v[52:53], v[52:53], 0, v[66:67]
	global_load_dword v223, v[52:53], off
	v_or_b32_e32 v50, 17, v60
	v_ashrrev_i32_e32 v51, 31, v50
	v_lshlrev_b64 v[50:51], 12, v[50:51]
	s_waitcnt vmcnt(1)
	v_lshlrev_b32_e32 v48, 16, v222
	v_mul_f32_e32 v69, 0x3fd744fd, v48
	v_lshl_add_u64 v[48:49], v[62:63], 0, v[50:51]
	global_load_ushort v224, v[48:49], off
	s_waitcnt vmcnt(1)
	v_fmac_f32_e32 v69, v44, v223
	v_lshl_add_u64 v[50:51], v[62:63], 0, v[56:57]
	global_load_ushort v225, v[50:51], off
	s_waitcnt vmcnt(1)
	v_lshlrev_b32_e32 v44, 16, v224
	v_mul_f32_e32 v75, 0x3fd744fd, v44
	v_fmac_f32_e32 v75, v45, v223
	s_waitcnt vmcnt(0)
	v_lshlrev_b32_e32 v44, 16, v225
	v_mul_f32_e32 v56, 0x3fd744fd, v44
	v_lshl_add_u64 v[44:45], v[62:63], 0, v[58:59]
	global_load_ushort v226, v[44:45], off
	global_load_dword v227, v[52:53], off offset:64
	global_load_ushort v228, v[54:55], off offset:32
	global_load_ushort v229, v[48:49], off offset:32
	global_load_ushort v230, v[50:51], off offset:32
	global_load_ushort v231, v[44:45], off offset:32
	global_load_dword v232, v[52:53], off offset:128
	global_load_ushort v233, v[54:55], off offset:64
	global_load_ushort v234, v[48:49], off offset:64
	global_load_ushort v235, v[50:51], off offset:64
	global_load_ushort v236, v[44:45], off offset:64
	global_load_dword v237, v[52:53], off offset:192
	global_load_ushort v238, v[54:55], off offset:96
	global_load_ushort v239, v[48:49], off offset:96
	global_load_ushort v240, v[50:51], off offset:96
	global_load_ushort v241, v[44:45], off offset:96
	v_fmac_f32_e32 v56, v46, v223
	s_waitcnt vmcnt(15)
	v_lshlrev_b32_e32 v46, 16, v226
	v_mul_f32_e32 v46, 0x3fd744fd, v46
	v_fmac_f32_e32 v46, v47, v223
	v_cvt_pk_bf16_f32 v47, v69, s0
	ds_write_b16 v61, v47 offset:2304
	v_cvt_pk_bf16_f32 v47, v75, s0
	ds_write_b16 v61, v47 offset:2448
	v_cvt_pk_bf16_f32 v47, v56, s0
	v_cvt_pk_bf16_f32 v46, v46, s0
	ds_write_b16 v61, v47 offset:2592
	ds_write_b16 v61, v46 offset:2736
	s_waitcnt vmcnt(13)
	v_lshlrev_b32_e32 v47, 16, v228
	v_mul_f32_e32 v47, 0x3fd744fd, v47
	v_fmac_f32_e32 v47, v40, v227
	s_waitcnt vmcnt(12)
	v_lshlrev_b32_e32 v40, 16, v229
	v_mul_f32_e32 v40, 0x3fd744fd, v40
	v_fmac_f32_e32 v40, v41, v227
	v_cvt_pk_bf16_f32 v40, v40, s0
	ds_write_b16 v61, v40 offset:2480
	s_waitcnt vmcnt(11)
	v_lshlrev_b32_e32 v41, 16, v230
	v_mul_f32_e32 v41, 0x3fd744fd, v41
	v_fmac_f32_e32 v41, v42, v227
	v_cvt_pk_bf16_f32 v40, v41, s0
	ds_write_b16 v61, v40 offset:2624
	s_waitcnt vmcnt(10)
	v_lshlrev_b32_e32 v42, 16, v231
	v_mul_f32_e32 v42, 0x3fd744fd, v42
	v_fmac_f32_e32 v42, v43, v227
	v_cvt_pk_bf16_f32 v43, v47, s0
	v_cvt_pk_bf16_f32 v40, v42, s0
	ds_write_b16 v61, v43 offset:2336
	ds_write_b16 v61, v40 offset:2768
	s_waitcnt vmcnt(8)
	v_lshlrev_b32_e32 v41, 16, v233
	v_mul_f32_e32 v41, 0x3fd744fd, v41
	v_fmac_f32_e32 v41, v36, v232
	s_waitcnt vmcnt(7)
	v_lshlrev_b32_e32 v36, 16, v234
	v_mul_f32_e32 v36, 0x3fd744fd, v36
	v_fmac_f32_e32 v36, v37, v232
	v_cvt_pk_bf16_f32 v36, v36, s0
	ds_write_b16 v61, v36 offset:2512
	s_waitcnt vmcnt(6)
	v_lshlrev_b32_e32 v37, 16, v235
	v_mul_f32_e32 v37, 0x3fd744fd, v37
	v_fmac_f32_e32 v37, v38, v232
	v_cvt_pk_bf16_f32 v36, v37, s0
	ds_write_b16 v61, v36 offset:2656
	s_waitcnt vmcnt(5)
	v_lshlrev_b32_e32 v38, 16, v236
	v_mul_f32_e32 v38, 0x3fd744fd, v38
	v_fmac_f32_e32 v38, v39, v232
	v_cvt_pk_bf16_f32 v39, v41, s0
	v_cvt_pk_bf16_f32 v36, v38, s0
	ds_write_b16 v61, v39 offset:2368
	ds_write_b16 v61, v36 offset:2800
	v_or_b32_e32 v38, 34, v60
	v_ashrrev_i32_e32 v39, 31, v38
	v_lshlrev_b64 v[40:41], 12, v[38:39]
	v_or_b32_e32 v38, 35, v60
	v_ashrrev_i32_e32 v39, 31, v38
	v_lshlrev_b64 v[42:43], 12, v[38:39]
	s_waitcnt vmcnt(3)
	v_lshlrev_b32_e32 v37, 16, v238
	v_mul_f32_e32 v37, 0x3fd744fd, v37
	v_fmac_f32_e32 v37, v32, v237
	s_waitcnt vmcnt(2)
	v_lshlrev_b32_e32 v32, 16, v239
	v_mul_f32_e32 v32, 0x3fd744fd, v32
	v_fmac_f32_e32 v32, v33, v237
	v_cvt_pk_bf16_f32 v32, v32, s0
	ds_write_b16 v61, v32 offset:2544
	s_waitcnt vmcnt(1)
	v_lshlrev_b32_e32 v33, 16, v240
	v_mul_f32_e32 v33, 0x3fd744fd, v33
	v_fmac_f32_e32 v33, v34, v237
	v_cvt_pk_bf16_f32 v32, v33, s0
	ds_write_b16 v61, v32 offset:2688
	v_add_u32_e32 v33, 0xfffff020, v72
	v_lshrrev_b32_e32 v33, 12, v33
	v_add_u32_e32 v33, 1, v33
	s_waitcnt vmcnt(0)
	v_lshlrev_b32_e32 v34, 16, v241
	v_mul_f32_e32 v34, 0x3fd744fd, v34
	v_fmac_f32_e32 v34, v35, v237
	v_cvt_pk_bf16_f32 v32, v34, s0
	ds_write_b16 v61, v32 offset:2832
	v_or_b32_e32 v32, 32, v60
	v_cmp_lt_i32_e32 vcc, s9, v32
	v_cvt_pk_bf16_f32 v35, v37, s0
	ds_write_b16 v61, v35 offset:2400
	v_cndmask_b32_e32 v136, 0, v33, vcc
	v_ashrrev_i32_e32 v33, 31, v32
	v_lshl_add_u64 v[34:35], v[136:137], 0, s[0:1]
	v_lshlrev_b64 v[32:33], 12, v[32:33]
	v_mad_u64_u32 v[36:37], s[6:7], v34, s5, v[64:65]
	v_lshl_add_u64 v[38:39], v[62:63], 0, v[32:33]
	global_load_ushort v248, v[38:39], off
	v_mad_i32_i24 v37, v35, s5, v37
	v_lshl_add_u64 v[36:37], v[36:37], 0, v[66:67]
	global_load_dword v249, v[36:37], off
	v_or_b32_e32 v34, 33, v60
	v_ashrrev_i32_e32 v35, 31, v34
	v_lshlrev_b64 v[34:35], 12, v[34:35]
	s_waitcnt vmcnt(1)
	v_lshlrev_b32_e32 v32, 16, v248
	v_mul_f32_e32 v45, 0x3fd744fd, v32
	v_lshl_add_u64 v[32:33], v[62:63], 0, v[34:35]
	global_load_ushort v250, v[32:33], off
	s_waitcnt vmcnt(1)
	v_fmac_f32_e32 v45, v28, v249
	v_lshl_add_u64 v[34:35], v[62:63], 0, v[40:41]
	global_load_ushort v251, v[34:35], off
	s_waitcnt vmcnt(1)
	v_lshlrev_b32_e32 v28, 16, v250
	v_mul_f32_e32 v46, 0x3fd744fd, v28
	v_fmac_f32_e32 v46, v29, v249
	s_waitcnt vmcnt(0)
	v_lshlrev_b32_e32 v28, 16, v251
	v_mul_f32_e32 v40, 0x3fd744fd, v28
	v_lshl_add_u64 v[28:29], v[62:63], 0, v[42:43]
	global_load_ushort v252, v[28:29], off
	global_load_dword v253, v[36:37], off offset:64
	global_load_ushort v254, v[38:39], off offset:32
	global_load_ushort v255, v[32:33], off offset:32
	global_load_ushort v202, v[34:35], off offset:32
	global_load_ushort v203, v[28:29], off offset:32
	global_load_dword v204, v[36:37], off offset:128
	global_load_ushort v205, v[38:39], off offset:64
	global_load_ushort v206, v[32:33], off offset:64
	global_load_ushort v207, v[34:35], off offset:64
	global_load_ushort v208, v[28:29], off offset:64
	global_load_dword v209, v[36:37], off offset:192
	global_load_ushort v210, v[38:39], off offset:96
	global_load_ushort v211, v[32:33], off offset:96
	global_load_ushort v212, v[34:35], off offset:96
	global_load_ushort v213, v[28:29], off offset:96
	v_fmac_f32_e32 v40, v30, v249
	s_waitcnt vmcnt(15)
	v_lshlrev_b32_e32 v30, 16, v252
	v_mul_f32_e32 v30, 0x3fd744fd, v30
	v_fmac_f32_e32 v30, v31, v249
	v_cvt_pk_bf16_f32 v31, v45, s0
	ds_write_b16 v61, v31 offset:4608
	v_cvt_pk_bf16_f32 v31, v46, s0
	ds_write_b16 v61, v31 offset:4752
	v_cvt_pk_bf16_f32 v31, v40, s0
	v_cvt_pk_bf16_f32 v30, v30, s0
	ds_write_b16 v61, v31 offset:4896
	ds_write_b16 v61, v30 offset:5040
	s_waitcnt vmcnt(13)
	v_lshlrev_b32_e32 v31, 16, v254
	v_mul_f32_e32 v31, 0x3fd744fd, v31
	v_fmac_f32_e32 v31, v24, v253
	s_waitcnt vmcnt(12)
	v_lshlrev_b32_e32 v24, 16, v255
	v_mul_f32_e32 v24, 0x3fd744fd, v24
	v_fmac_f32_e32 v24, v25, v253
	v_cvt_pk_bf16_f32 v24, v24, s0
	ds_write_b16 v61, v24 offset:4784
	s_waitcnt vmcnt(11)
	v_lshlrev_b32_e32 v25, 16, v202
	v_mul_f32_e32 v25, 0x3fd744fd, v25
	v_fmac_f32_e32 v25, v26, v253
	v_cvt_pk_bf16_f32 v24, v25, s0
	ds_write_b16 v61, v24 offset:4928
	s_waitcnt vmcnt(10)
	v_lshlrev_b32_e32 v26, 16, v203
	v_mul_f32_e32 v26, 0x3fd744fd, v26
	v_fmac_f32_e32 v26, v27, v253
	v_cvt_pk_bf16_f32 v27, v31, s0
	v_cvt_pk_bf16_f32 v24, v26, s0
	ds_write_b16 v61, v27 offset:4640
	ds_write_b16 v61, v24 offset:5072
	s_waitcnt vmcnt(8)
	v_lshlrev_b32_e32 v25, 16, v205
	v_mul_f32_e32 v25, 0x3fd744fd, v25
	v_fmac_f32_e32 v25, v20, v204
	s_waitcnt vmcnt(7)
	v_lshlrev_b32_e32 v20, 16, v206
	v_mul_f32_e32 v20, 0x3fd744fd, v20
	v_fmac_f32_e32 v20, v21, v204
	v_cvt_pk_bf16_f32 v20, v20, s0
	ds_write_b16 v61, v20 offset:4816
	s_waitcnt vmcnt(6)
	v_lshlrev_b32_e32 v21, 16, v207
	v_mul_f32_e32 v21, 0x3fd744fd, v21
	v_fmac_f32_e32 v21, v22, v204
	v_cvt_pk_bf16_f32 v20, v21, s0
	ds_write_b16 v61, v20 offset:4960
	s_waitcnt vmcnt(5)
	v_lshlrev_b32_e32 v22, 16, v208
	v_mul_f32_e32 v22, 0x3fd744fd, v22
	v_fmac_f32_e32 v22, v23, v204
	v_cvt_pk_bf16_f32 v23, v25, s0
	v_cvt_pk_bf16_f32 v20, v22, s0
	ds_write_b16 v61, v23 offset:4672
	ds_write_b16 v61, v20 offset:5104
	v_or_b32_e32 v22, 50, v60
	v_ashrrev_i32_e32 v23, 31, v22
	v_lshlrev_b64 v[24:25], 12, v[22:23]
	v_or_b32_e32 v22, 51, v60
	v_ashrrev_i32_e32 v23, 31, v22
	v_lshlrev_b64 v[26:27], 12, v[22:23]
	s_waitcnt vmcnt(3)
	v_lshlrev_b32_e32 v21, 16, v210
	v_mul_f32_e32 v21, 0x3fd744fd, v21
	v_fmac_f32_e32 v21, v16, v209
	s_waitcnt vmcnt(2)
	v_lshlrev_b32_e32 v16, 16, v211
	v_mul_f32_e32 v16, 0x3fd744fd, v16
	v_fmac_f32_e32 v16, v17, v209
	v_cvt_pk_bf16_f32 v16, v16, s0
	ds_write_b16 v61, v16 offset:4848
	s_waitcnt vmcnt(1)
	v_lshlrev_b32_e32 v17, 16, v212
	v_mul_f32_e32 v17, 0x3fd744fd, v17
	v_fmac_f32_e32 v17, v18, v209
	v_cvt_pk_bf16_f32 v16, v17, s0
	ds_write_b16 v61, v16 offset:4992
	v_add_u32_e32 v17, 0xfffff030, v72
	v_lshrrev_b32_e32 v17, 12, v17
	v_add_u32_e32 v17, 1, v17
	s_waitcnt vmcnt(0)
	v_lshlrev_b32_e32 v18, 16, v213
	v_mul_f32_e32 v18, 0x3fd744fd, v18
	v_fmac_f32_e32 v18, v19, v209
	v_cvt_pk_bf16_f32 v16, v18, s0
	ds_write_b16 v61, v16 offset:5136
	v_or_b32_e32 v16, 48, v60
	v_cmp_lt_i32_e32 vcc, s9, v16
	v_cvt_pk_bf16_f32 v19, v21, s0
	ds_write_b16 v61, v19 offset:4704
	v_cndmask_b32_e32 v136, 0, v17, vcc
	v_ashrrev_i32_e32 v17, 31, v16
	v_lshl_add_u64 v[18:19], v[136:137], 0, s[0:1]
	v_lshlrev_b64 v[16:17], 12, v[16:17]
	v_mad_u64_u32 v[20:21], s[6:7], v18, s5, v[64:65]
	v_lshl_add_u64 v[22:23], v[62:63], 0, v[16:17]
	global_load_ushort v214, v[22:23], off
	v_mad_i32_i24 v21, v19, s5, v21
	v_lshl_add_u64 v[20:21], v[20:21], 0, v[66:67]
	global_load_dword v215, v[20:21], off
	v_or_b32_e32 v18, 49, v60
	v_ashrrev_i32_e32 v19, 31, v18
	v_lshlrev_b64 v[18:19], 12, v[18:19]
	s_ashr_i32 s5, s4, 31
	s_lshl_b64 s[4:5], s[4:5], 1
	s_add_u32 s4, s46, s4
	s_addc_u32 s5, s47, s5
	v_lshlrev_b32_e32 v136, 1, v73
	s_add_i32 s8, s8, 1
	s_mov_b64 s[6:7], 0
	s_waitcnt vmcnt(1)
	v_lshlrev_b32_e32 v16, 16, v214
	v_mul_f32_e32 v29, 0x3fd744fd, v16
	v_lshl_add_u64 v[16:17], v[62:63], 0, v[18:19]
	global_load_ushort v216, v[16:17], off
	s_waitcnt vmcnt(1)
	v_fmac_f32_e32 v29, v12, v215
	v_lshl_add_u64 v[18:19], v[62:63], 0, v[24:25]
	global_load_ushort v217, v[18:19], off
	s_waitcnt vmcnt(1)
	v_lshlrev_b32_e32 v12, 16, v216
	v_mul_f32_e32 v30, 0x3fd744fd, v12
	v_fmac_f32_e32 v30, v13, v215
	s_waitcnt vmcnt(0)
	v_lshlrev_b32_e32 v12, 16, v217
	v_mul_f32_e32 v24, 0x3fd744fd, v12
	v_lshl_add_u64 v[12:13], v[62:63], 0, v[26:27]
	global_load_ushort v218, v[12:13], off
	global_load_dword v219, v[20:21], off offset:64
	global_load_ushort v220, v[22:23], off offset:32
	global_load_ushort v221, v[16:17], off offset:32
	global_load_ushort v222, v[18:19], off offset:32
	global_load_ushort v223, v[12:13], off offset:32
	global_load_dword v224, v[20:21], off offset:128
	global_load_ushort v225, v[22:23], off offset:64
	global_load_ushort v226, v[16:17], off offset:64
	global_load_ushort v227, v[18:19], off offset:64
	global_load_ushort v228, v[12:13], off offset:64
	global_load_dword v229, v[20:21], off offset:192
	global_load_ushort v230, v[22:23], off offset:96
	global_load_ushort v231, v[16:17], off offset:96
	global_load_ushort v232, v[18:19], off offset:96
	global_load_ushort v233, v[12:13], off offset:96
	v_fmac_f32_e32 v24, v14, v215
	s_waitcnt vmcnt(15)
	v_lshlrev_b32_e32 v14, 16, v218
	v_mul_f32_e32 v14, 0x3fd744fd, v14
	v_fmac_f32_e32 v14, v15, v215
	v_cvt_pk_bf16_f32 v15, v29, s0
	ds_write_b16 v61, v15 offset:6912
	v_cvt_pk_bf16_f32 v15, v30, s0
	ds_write_b16 v61, v15 offset:7056
	v_cvt_pk_bf16_f32 v15, v24, s0
	v_cvt_pk_bf16_f32 v14, v14, s0
	ds_write_b16 v61, v15 offset:7200
	ds_write_b16 v61, v14 offset:7344
	s_waitcnt vmcnt(13)
	v_lshlrev_b32_e32 v15, 16, v220
	v_mul_f32_e32 v15, 0x3fd744fd, v15
	v_fmac_f32_e32 v15, v8, v219
	s_waitcnt vmcnt(12)
	v_lshlrev_b32_e32 v8, 16, v221
	v_mul_f32_e32 v8, 0x3fd744fd, v8
	v_fmac_f32_e32 v8, v9, v219
	v_cvt_pk_bf16_f32 v8, v8, s0
	ds_write_b16 v61, v8 offset:7088
	s_waitcnt vmcnt(11)
	v_lshlrev_b32_e32 v9, 16, v222
	v_mul_f32_e32 v9, 0x3fd744fd, v9
	v_fmac_f32_e32 v9, v10, v219
	v_cvt_pk_bf16_f32 v8, v9, s0
	ds_write_b16 v61, v8 offset:7232
	s_waitcnt vmcnt(10)
	v_lshlrev_b32_e32 v10, 16, v223
	v_mul_f32_e32 v10, 0x3fd744fd, v10
	v_fmac_f32_e32 v10, v11, v219
	v_cvt_pk_bf16_f32 v11, v15, s0
	v_cvt_pk_bf16_f32 v8, v10, s0
	ds_write_b16 v61, v11 offset:6944
	ds_write_b16 v61, v8 offset:7376
	s_waitcnt vmcnt(8)
	v_lshlrev_b32_e32 v9, 16, v225
	v_mul_f32_e32 v9, 0x3fd744fd, v9
	v_fmac_f32_e32 v9, v4, v224
	s_waitcnt vmcnt(7)
	v_lshlrev_b32_e32 v4, 16, v226
	v_mul_f32_e32 v4, 0x3fd744fd, v4
	v_fmac_f32_e32 v4, v5, v224
	v_cvt_pk_bf16_f32 v4, v4, s0
	ds_write_b16 v61, v4 offset:7120
	s_waitcnt vmcnt(6)
	v_lshlrev_b32_e32 v5, 16, v227
	v_mul_f32_e32 v5, 0x3fd744fd, v5
	v_fmac_f32_e32 v5, v6, v224
	v_cvt_pk_bf16_f32 v4, v5, s0
	ds_write_b16 v61, v4 offset:7264
	s_waitcnt vmcnt(5)
	v_lshlrev_b32_e32 v6, 16, v228
	v_mul_f32_e32 v6, 0x3fd744fd, v6
	v_fmac_f32_e32 v6, v7, v224
	v_cvt_pk_bf16_f32 v7, v9, s0
	v_cvt_pk_bf16_f32 v4, v6, s0
	ds_write_b16 v61, v7 offset:6976
	ds_write_b16 v61, v4 offset:7408
	s_waitcnt vmcnt(3)
	v_lshlrev_b32_e32 v5, 16, v230
	v_mul_f32_e32 v5, 0x3fd744fd, v5
	v_fmac_f32_e32 v5, v0, v229
	s_waitcnt vmcnt(2)
	v_lshlrev_b32_e32 v0, 16, v231
	v_mul_f32_e32 v0, 0x3fd744fd, v0
	v_fmac_f32_e32 v0, v1, v229
	v_cvt_pk_bf16_f32 v0, v0, s0
	ds_write_b16 v61, v0 offset:7152
	s_waitcnt vmcnt(1)
	v_lshlrev_b32_e32 v1, 16, v232
	v_mul_f32_e32 v1, 0x3fd744fd, v1
	v_fmac_f32_e32 v1, v2, v229
	v_cvt_pk_bf16_f32 v0, v1, s0
	ds_write_b16 v61, v0 offset:7296
	v_mov_b32_e32 v1, v137
	s_waitcnt vmcnt(0)
	v_lshlrev_b32_e32 v2, 16, v233
	v_mul_f32_e32 v2, 0x3fd744fd, v2
	v_fmac_f32_e32 v2, v3, v229
	v_cvt_pk_bf16_f32 v0, v2, s0
	ds_write_b16 v61, v0 offset:7440
	v_lshlrev_b32_e32 v0, 4, v71
	v_cvt_pk_bf16_f32 v3, v5, s0
	v_and_b32_e32 v0, 0x70, v0
	ds_write_b16 v61, v3 offset:7008
	v_or_b32_e32 v6, v74, v0
	v_lshl_add_u64 v[2:3], s[4:5], 0, v[136:137]
	s_movk_i32 s4, 0x90
	v_mad_u32_u24 v10, v70, s4, v6
	v_lshl_add_u64 v[4:5], v[2:3], 0, v[0:1]
	ds_read_b128 v[0:3], v10
	v_or_b32_e32 v6, v72, v70
	v_ashrrev_i32_e32 v7, 31, v6
	v_lshlrev_b64 v[8:9], 12, v[6:7]
	v_lshl_add_u64 v[8:9], v[4:5], 0, v[8:9]
	s_waitcnt lgkmcnt(0)
	global_store_dwordx4 v[8:9], v[0:3], off offset:2048
	ds_read_b128 v[0:3], v10 offset:1152
	v_or_b32_e32 v8, 8, v6
	v_ashrrev_i32_e32 v9, 31, v8
	v_lshlrev_b64 v[8:9], 12, v[8:9]
	v_lshl_add_u64 v[8:9], v[4:5], 0, v[8:9]
	s_waitcnt lgkmcnt(0)
	global_store_dwordx4 v[8:9], v[0:3], off offset:2048
	ds_read_b128 v[0:3], v10 offset:2304
	v_or_b32_e32 v8, 16, v6
	v_ashrrev_i32_e32 v9, 31, v8
	v_lshlrev_b64 v[8:9], 12, v[8:9]
	v_lshl_add_u64 v[8:9], v[4:5], 0, v[8:9]
	s_waitcnt lgkmcnt(0)
	global_store_dwordx4 v[8:9], v[0:3], off offset:2048
	ds_read_b128 v[0:3], v10 offset:3456
	v_or_b32_e32 v8, 24, v6
	v_ashrrev_i32_e32 v9, 31, v8
	v_lshlrev_b64 v[8:9], 12, v[8:9]
	v_lshl_add_u64 v[8:9], v[4:5], 0, v[8:9]
	s_waitcnt lgkmcnt(0)
	global_store_dwordx4 v[8:9], v[0:3], off offset:2048
	ds_read_b128 v[0:3], v10 offset:4608
	v_or_b32_e32 v8, 32, v6
	v_ashrrev_i32_e32 v9, 31, v8
	v_lshlrev_b64 v[8:9], 12, v[8:9]
	v_lshl_add_u64 v[8:9], v[4:5], 0, v[8:9]
	s_waitcnt lgkmcnt(0)
	global_store_dwordx4 v[8:9], v[0:3], off offset:2048
	ds_read_b128 v[0:3], v10 offset:5760
	v_or_b32_e32 v8, 40, v6
	v_ashrrev_i32_e32 v9, 31, v8
	v_lshlrev_b64 v[8:9], 12, v[8:9]
	v_lshl_add_u64 v[8:9], v[4:5], 0, v[8:9]
	s_waitcnt lgkmcnt(0)
	global_store_dwordx4 v[8:9], v[0:3], off offset:2048
	ds_read_b128 v[0:3], v10 offset:6912
	v_or_b32_e32 v8, 48, v6
	v_ashrrev_i32_e32 v9, 31, v8
	v_lshlrev_b64 v[8:9], 12, v[8:9]
	v_lshl_add_u64 v[8:9], v[4:5], 0, v[8:9]
	s_waitcnt lgkmcnt(0)
	global_store_dwordx4 v[8:9], v[0:3], off offset:2048
	ds_read_b128 v[0:3], v10 offset:8064
	v_or_b32_e32 v6, 56, v6
	v_ashrrev_i32_e32 v7, 31, v6
	v_lshlrev_b64 v[6:7], 12, v[6:7]
	v_lshl_add_u64 v[4:5], v[4:5], 0, v[6:7]
	s_waitcnt lgkmcnt(0)
	global_store_dwordx4 v[4:5], v[0:3], off offset:2048
	s_barrier
	s_branch .LBB0_52

.LBB0_149:
	s_mov_b64 s[4:5], -1
	s_and_b64 vcc, exec, s[0:1]
	s_cbranch_vccz .LBB0_141
	v_mov_b32_e32 v69, v139
	v_readlane_b32 s36, v246, 9
	v_ashrrev_i32_e32 v72, 6, v69
	s_waitcnt vmcnt(48)
	v_lshlrev_b32_e32 v6, 3, v72
	v_bfe_u32 v68, v69, 3, 3
	v_or_b32_e32 v2, v6, v68
	v_lshrrev_b32_e32 v7, 1, v2
	s_lshl_b32 s1, s7, 7
	v_xor_b32_e32 v3, v7, v69
	v_readlane_b32 s50, v246, 23
	v_readlane_b32 s51, v246, 24
	s_lshl_b32 s0, s8, 7
	v_add_u32_e32 v4, s1, v2
	s_movk_i32 s7, 0x880
	v_readlane_b32 s37, v246, 10
	v_mov_b64_e32 v[0:1], s[50:51]
	v_lshlrev_b32_e32 v3, 4, v3
	v_mad_i64_i32 v[0:1], s[4:5], v4, s7, v[0:1]
	v_and_b32_e32 v136, 0x70, v3
	v_add_u32_e32 v4, s0, v2
	v_mov_b64_e32 v[2:3], s[36:37]
	v_mad_i64_i32 v[2:3], s[4:5], v4, s7, v[2:3]
	v_lshlrev_b32_e32 v74, 10, v72
	v_add_u32_e32 v4, 0x4000, v74
	v_readfirstlane_b32 s4, v74
	v_lshl_add_u64 v[0:1], v[0:1], 0, v[136:137]
	s_mov_b32 m0, s4
	v_readfirstlane_b32 s4, v4
	v_add_u32_e32 v9, 0x1000, v74
	v_lshl_add_u64 v[2:3], v[2:3], 0, v[136:137]
	global_load_lds_dwordx4 v[0:1], off
	s_mov_b32 m0, s4
	s_mov_b64 s[8:9], 0x11000
	v_readfirstlane_b32 s4, v9
	v_add_u32_e32 v9, 0x5000, v74
	global_load_lds_dwordx4 v[2:3], off
	v_lshl_add_u64 v[4:5], v[0:1], 0, s[8:9]
	s_mov_b32 m0, s4
	v_readfirstlane_b32 s4, v9
	v_add_u32_e32 v9, 0x2000, v74
	global_load_lds_dwordx4 v[4:5], off
	v_lshl_add_u64 v[4:5], v[2:3], 0, s[8:9]
	s_mov_b32 m0, s4
	s_mov_b64 s[8:9], 0x22000
	v_readfirstlane_b32 s4, v9
	v_add_u32_e32 v9, 0x6000, v74
	global_load_lds_dwordx4 v[4:5], off
	v_lshl_add_u64 v[4:5], v[0:1], 0, s[8:9]
	s_mov_b32 m0, s4
	v_readfirstlane_b32 s4, v9
	global_load_lds_dwordx4 v[4:5], off
	v_lshl_add_u64 v[4:5], v[2:3], 0, s[8:9]
	s_mov_b32 m0, s4
	s_mov_b64 s[8:9], 0x33000
	global_load_lds_dwordx4 v[4:5], off
	v_add_u32_e32 v4, 0x3000, v74
	v_lshl_add_u64 v[0:1], v[0:1], 0, s[8:9]
	v_readfirstlane_b32 s4, v4
	s_mov_b32 m0, s4
	v_bfe_u32 v71, v69, 4, 2
	global_load_lds_dwordx4 v[0:1], off
	v_lshl_add_u64 v[0:1], v[2:3], 0, s[8:9]
	v_add_u32_e32 v2, 0x7000, v74
	v_and_b32_e32 v73, 15, v69
	v_readfirstlane_b32 s4, v2
	s_mov_b32 m0, s4
	v_lshrrev_b32_e32 v8, 1, v69
	global_load_lds_dwordx4 v[0:1], off
	v_ashrrev_i32_e32 v1, 1, v69
	v_bfe_u32 v0, v69, 1, 3
	v_and_b32_e32 v70, 0xffffffc0, v1
	v_or_b32_e32 v1, v70, v73
	v_bitop3_b32 v0, v71, v0, 4 bitop3:0x36
	v_lshlrev_b32_e32 v75, 7, v1
	v_bitop3_b32 v1, v71, v8, 7 bitop3:0x78
	v_lshlrev_b32_e32 v78, 4, v0
	v_or_b32_e32 v0, s1, v68
	v_lshlrev_b32_e32 v76, 4, v1
	v_lshlrev_b32_e32 v1, 7, v69
	v_add_u32_e32 v0, v0, v6
	v_bitop3_b32 v2, v7, 7, v69 bitop3:0x48
	v_and_b32_e32 v77, 0x2780, v1
	v_mad_i64_i32 v[0:1], s[4:5], v0, s7, 0
	v_lshlrev_b32_e32 v2, 4, v2
	v_or_b32_e32 v0, v0, v2
	v_lshl_add_u64 v[64:65], s[50:51], 0, v[0:1]
	v_or_b32_e32 v0, s0, v68
	v_add_u32_e32 v0, v0, v6
	v_mad_i64_i32 v[0:1], s[4:5], v0, s7, 0
	s_waitcnt vmcnt(0)
	v_or_b32_e32 v0, v0, v2
	v_lshl_add_u64 v[66:67], s[36:37], 0, v[0:1]
	v_mov_b32_e32 v0, 0
	s_mov_b32 s7, 0
	s_mov_b64 s[4:5], 0
	v_mov_b32_e32 v1, v0
	v_mov_b32_e32 v2, v0
	v_mov_b32_e32 v3, v0
	v_mov_b32_e32 v4, v0
	v_mov_b32_e32 v5, v0
	v_mov_b32_e32 v6, v0
	v_mov_b32_e32 v7, v0
	v_mov_b32_e32 v8, v0
	v_mov_b32_e32 v9, v0
	v_mov_b32_e32 v10, v0
	v_mov_b32_e32 v11, v0
	s_waitcnt vmcnt(0)
	v_mov_b32_e32 v12, v0
	v_mov_b32_e32 v13, v0
	v_mov_b32_e32 v14, v0
	v_mov_b32_e32 v15, v0
	v_mov_b32_e32 v16, v0
	v_mov_b32_e32 v17, v0
	v_mov_b32_e32 v18, v0
	v_mov_b32_e32 v19, v0
	v_mov_b32_e32 v20, v0
	v_mov_b32_e32 v21, v0
	v_mov_b32_e32 v22, v0
	v_mov_b32_e32 v23, v0
	v_mov_b32_e32 v24, v0
	v_mov_b32_e32 v25, v0
	v_mov_b32_e32 v26, v0
	v_mov_b32_e32 v27, v0
	v_mov_b32_e32 v28, v0
	v_mov_b32_e32 v29, v0
	v_mov_b32_e32 v30, v0
	v_mov_b32_e32 v31, v0
	v_mov_b32_e32 v32, v0
	v_mov_b32_e32 v33, v0
	v_mov_b32_e32 v34, v0
	v_mov_b32_e32 v35, v0
	v_mov_b32_e32 v36, v0
	v_mov_b32_e32 v37, v0
	v_mov_b32_e32 v38, v0
	v_mov_b32_e32 v39, v0
	v_mov_b32_e32 v40, v0
	v_mov_b32_e32 v41, v0
	v_mov_b32_e32 v42, v0
	v_mov_b32_e32 v43, v0
	v_mov_b32_e32 v44, v0
	v_mov_b32_e32 v45, v0
	v_mov_b32_e32 v46, v0
	v_mov_b32_e32 v47, v0
	v_mov_b32_e32 v48, v0
	v_mov_b32_e32 v49, v0
	v_mov_b32_e32 v50, v0
	v_mov_b32_e32 v51, v0
	v_mov_b32_e32 v52, v0
	v_mov_b32_e32 v53, v0
	v_mov_b32_e32 v54, v0
	v_mov_b32_e32 v55, v0
	v_mov_b32_e32 v56, v0
	v_mov_b32_e32 v57, v0
	v_mov_b32_e32 v58, v0
	v_mov_b32_e32 v59, v0
	v_mov_b32_e32 v60, v0
	v_mov_b32_e32 v61, v0
	v_mov_b32_e32 v62, v0
	v_mov_b32_e32 v63, v0
	s_mov_b64 s[10:11], 0x11080
	s_mov_b64 s[12:13], 0x33080
	s_mov_b64 s[14:15], 0x22080
	v_readlane_b32 s38, v246, 11
	v_readlane_b32 s39, v246, 12
	v_readlane_b32 s40, v246, 13
	v_readlane_b32 s41, v246, 14
	v_readlane_b32 s42, v246, 15
	v_readlane_b32 s43, v246, 16
	v_readlane_b32 s44, v246, 17
	v_readlane_b32 s45, v246, 18
	v_readlane_b32 s46, v246, 19
	v_readlane_b32 s47, v246, 20
	v_readlane_b32 s48, v246, 21
	v_readlane_b32 s49, v246, 22
	s_waitcnt vmcnt(0) lgkmcnt(0)
	s_barrier
	s_bitcmp1_b32 s68, 8
	s_cbranch_scc0 gp151_skip
	s_setprio 1
gp151_skip:
.LBB0_151:
	s_and_b32 s8, s7, 0x8000
	s_xor_b32 s9, s8, 0x8000
	v_add_u32_e32 v79, s9, v74
	v_lshl_add_u64 v[80:81], v[64:65], 0, s[4:5]
	v_readfirstlane_b32 s9, v79
	v_lshl_add_u64 v[82:83], v[80:81], 0, s[28:29]
	s_mov_b32 m0, s9
	v_lshl_add_u64 v[84:85], v[66:67], 0, s[4:5]
	global_load_lds_dwordx4 v[82:83], off
	v_add_u32_e32 v82, 0x4000, v79
	v_lshl_add_u64 v[86:87], v[84:85], 0, s[28:29]
	v_readfirstlane_b32 s9, v82
	s_mov_b32 m0, s9
	v_lshl_add_u64 v[82:83], v[80:81], 0, s[10:11]
	global_load_lds_dwordx4 v[86:87], off
	v_add_u32_e32 v86, 0x1000, v79
	s_nop 0
	v_readfirstlane_b32 s9, v86
	v_add_u32_e32 v86, 0x5000, v79
	s_mov_b32 m0, s9
	v_readfirstlane_b32 s9, v86
	v_add_u32_e32 v86, 0x2000, v79
	global_load_lds_dwordx4 v[82:83], off
	v_lshl_add_u64 v[82:83], v[84:85], 0, s[10:11]
	s_mov_b32 m0, s9
	v_readfirstlane_b32 s9, v86
	v_add_u32_e32 v86, 0x6000, v79
	global_load_lds_dwordx4 v[82:83], off
	v_lshl_add_u64 v[82:83], v[80:81], 0, s[14:15]
	s_mov_b32 m0, s9
	v_readfirstlane_b32 s9, v86
	global_load_lds_dwordx4 v[82:83], off
	v_lshl_add_u64 v[82:83], v[84:85], 0, s[14:15]
	s_mov_b32 m0, s9
	v_lshl_add_u64 v[80:81], v[80:81], 0, s[12:13]
	global_load_lds_dwordx4 v[82:83], off
	v_add_u32_e32 v82, 0x3000, v79
	v_add_u32_e32 v79, 0x7000, v79
	v_readfirstlane_b32 s9, v82
	s_mov_b32 m0, s9
	v_readfirstlane_b32 s9, v79
	global_load_lds_dwordx4 v[80:81], off
	v_lshl_add_u64 v[80:81], v[84:85], 0, s[12:13]
	s_mov_b32 m0, s9
	v_or_b32_e32 v79, s8, v76
	global_load_lds_dwordx4 v[80:81], off
	v_add_u32_e32 v100, v79, v75
	v_add_u32_e32 v79, v79, v77
	ds_read_b128 v[80:83], v100
	ds_read_b128 v[84:87], v100 offset:2048
	ds_read_b128 v[88:91], v79 offset:16384
	ds_read_b128 v[92:95], v79 offset:18432
	ds_read_b128 v[96:99], v100 offset:4096
	ds_read_b128 v[100:103], v100 offset:6144
	ds_read_b128 v[104:107], v79 offset:20480
	ds_read_b128 v[108:111], v79 offset:22528
	v_or_b32_e32 v79, s8, v78
	v_add_u32_e32 v132, v79, v75
	v_add_u32_e32 v79, v79, v77
	ds_read_b128 v[112:115], v132
	ds_read_b128 v[116:119], v132 offset:2048
	ds_read_b128 v[120:123], v79 offset:16384
	ds_read_b128 v[124:127], v79 offset:18432
	ds_read_b128 v[128:131], v132 offset:4096
	ds_read_b128 v[132:135], v132 offset:6144
	ds_read_b128 v[146:149], v79 offset:20480
	ds_read_b128 v[150:153], v79 offset:22528
	s_waitcnt lgkmcnt(0)
	v_mfma_f32_16x16x32_bf16 v[60:63], v[80:83], v[88:91], v[60:63]
	v_mfma_f32_16x16x32_bf16 v[56:59], v[80:83], v[92:95], v[56:59]
	v_mfma_f32_16x16x32_bf16 v[52:55], v[80:83], v[104:107], v[52:55]
	v_mfma_f32_16x16x32_bf16 v[48:51], v[80:83], v[108:111], v[48:51]
	v_mfma_f32_16x16x32_bf16 v[44:47], v[84:87], v[88:91], v[44:47]
	v_mfma_f32_16x16x32_bf16 v[40:43], v[84:87], v[92:95], v[40:43]
	v_mfma_f32_16x16x32_bf16 v[36:39], v[84:87], v[104:107], v[36:39]
	v_mfma_f32_16x16x32_bf16 v[32:35], v[84:87], v[108:111], v[32:35]
	v_mfma_f32_16x16x32_bf16 v[28:31], v[96:99], v[88:91], v[28:31]
	v_mfma_f32_16x16x32_bf16 v[24:27], v[96:99], v[92:95], v[24:27]
	v_mfma_f32_16x16x32_bf16 v[20:23], v[96:99], v[104:107], v[20:23]
	v_mfma_f32_16x16x32_bf16 v[16:19], v[96:99], v[108:111], v[16:19]
	v_mfma_f32_16x16x32_bf16 v[12:15], v[100:103], v[88:91], v[12:15]
	v_mfma_f32_16x16x32_bf16 v[8:11], v[100:103], v[92:95], v[8:11]
	v_mfma_f32_16x16x32_bf16 v[4:7], v[100:103], v[104:107], v[4:7]
	v_mfma_f32_16x16x32_bf16 v[0:3], v[100:103], v[108:111], v[0:3]
	v_mfma_f32_16x16x32_bf16 v[60:63], v[112:115], v[120:123], v[60:63]
	v_mfma_f32_16x16x32_bf16 v[56:59], v[112:115], v[124:127], v[56:59]
	v_mfma_f32_16x16x32_bf16 v[52:55], v[112:115], v[146:149], v[52:55]
	v_mfma_f32_16x16x32_bf16 v[48:51], v[112:115], v[150:153], v[48:51]
	v_mfma_f32_16x16x32_bf16 v[44:47], v[116:119], v[120:123], v[44:47]
	v_mfma_f32_16x16x32_bf16 v[40:43], v[116:119], v[124:127], v[40:43]
	v_mfma_f32_16x16x32_bf16 v[36:39], v[116:119], v[146:149], v[36:39]
	v_mfma_f32_16x16x32_bf16 v[32:35], v[116:119], v[150:153], v[32:35]
	v_mfma_f32_16x16x32_bf16 v[28:31], v[128:131], v[120:123], v[28:31]
	v_mfma_f32_16x16x32_bf16 v[24:27], v[128:131], v[124:127], v[24:27]
	v_mfma_f32_16x16x32_bf16 v[20:23], v[128:131], v[146:149], v[20:23]
	v_mfma_f32_16x16x32_bf16 v[16:19], v[128:131], v[150:153], v[16:19]
	v_mfma_f32_16x16x32_bf16 v[12:15], v[132:135], v[120:123], v[12:15]
	v_mfma_f32_16x16x32_bf16 v[8:11], v[132:135], v[124:127], v[8:11]
	v_mfma_f32_16x16x32_bf16 v[4:7], v[132:135], v[146:149], v[4:7]
	v_mfma_f32_16x16x32_bf16 v[0:3], v[132:135], v[150:153], v[0:3]
	s_add_i32 s7, s7, 0x8000
	s_waitcnt vmcnt(0)
	s_add_u32 s4, s4, 0x80
	s_addc_u32 s5, s5, 0
	s_cmpk_lg_i32 s4, 0x780
	s_barrier
	s_cbranch_scc1 .LBB0_151
	s_setprio 0
	v_add_u32_e32 v74, v78, v77
	v_add_u32_e32 v102, v78, v75
	v_add_u32_e32 v122, v76, v77
	v_add_u32_e32 v130, v76, v75
	ds_read_b128 v[64:67], v74 offset:55296
	ds_read_b128 v[78:81], v74 offset:53248
	ds_read_b128 v[82:85], v102 offset:38912
	ds_read_b128 v[86:89], v102 offset:36864
	ds_read_b128 v[90:93], v74 offset:51200
	ds_read_b128 v[94:97], v74 offset:49152
	ds_read_b128 v[98:101], v102 offset:34816
	ds_read_b128 v[102:105], v102 offset:32768
	ds_read_b128 v[74:77], v122 offset:55296
	ds_read_b128 v[106:109], v122 offset:53248
	ds_read_b128 v[110:113], v130 offset:38912
	ds_read_b128 v[114:117], v130 offset:36864
	ds_read_b128 v[118:121], v122 offset:51200
	ds_read_b128 v[122:125], v122 offset:49152
	ds_read_b128 v[126:129], v130 offset:34816
	ds_read_b128 v[130:133], v130 offset:32768
	v_and_b32_e32 v134, 64, v69
	s_waitcnt lgkmcnt(0)
	v_mfma_f32_16x16x32_bf16 v[60:63], v[130:133], v[122:125], v[60:63]
	v_mfma_f32_16x16x32_bf16 v[56:59], v[130:133], v[118:121], v[56:59]
	v_mfma_f32_16x16x32_bf16 v[52:55], v[130:133], v[106:109], v[52:55]
	v_mfma_f32_16x16x32_bf16 v[48:51], v[130:133], v[74:77], v[48:51]
	v_mfma_f32_16x16x32_bf16 v[44:47], v[126:129], v[122:125], v[44:47]
	v_mfma_f32_16x16x32_bf16 v[40:43], v[126:129], v[118:121], v[40:43]
	v_mfma_f32_16x16x32_bf16 v[36:39], v[126:129], v[106:109], v[36:39]
	v_mfma_f32_16x16x32_bf16 v[32:35], v[126:129], v[74:77], v[32:35]
	v_mfma_f32_16x16x32_bf16 v[28:31], v[114:117], v[122:125], v[28:31]
	v_mfma_f32_16x16x32_bf16 v[24:27], v[114:117], v[118:121], v[24:27]
	v_mfma_f32_16x16x32_bf16 v[20:23], v[114:117], v[106:109], v[20:23]
	v_mfma_f32_16x16x32_bf16 v[16:19], v[114:117], v[74:77], v[16:19]
	v_mfma_f32_16x16x32_bf16 v[12:15], v[110:113], v[122:125], v[12:15]
	v_mfma_f32_16x16x32_bf16 v[8:11], v[110:113], v[118:121], v[8:11]
	v_mfma_f32_16x16x32_bf16 v[4:7], v[110:113], v[106:109], v[4:7]
	v_mfma_f32_16x16x32_bf16 v[0:3], v[110:113], v[74:77], v[0:3]
	v_mfma_f32_16x16x32_bf16 v[60:63], v[102:105], v[94:97], v[60:63]
	v_mfma_f32_16x16x32_bf16 v[56:59], v[102:105], v[90:93], v[56:59]
	v_mfma_f32_16x16x32_bf16 v[52:55], v[102:105], v[78:81], v[52:55]
	v_mfma_f32_16x16x32_bf16 v[48:51], v[102:105], v[64:67], v[48:51]
	v_mfma_f32_16x16x32_bf16 v[44:47], v[98:101], v[94:97], v[44:47]
	v_mfma_f32_16x16x32_bf16 v[40:43], v[98:101], v[90:93], v[40:43]
	v_mfma_f32_16x16x32_bf16 v[36:39], v[98:101], v[78:81], v[36:39]
	v_mfma_f32_16x16x32_bf16 v[32:35], v[98:101], v[64:67], v[32:35]
	v_mfma_f32_16x16x32_bf16 v[28:31], v[86:89], v[94:97], v[28:31]
	v_mfma_f32_16x16x32_bf16 v[24:27], v[86:89], v[90:93], v[24:27]
	v_mfma_f32_16x16x32_bf16 v[20:23], v[86:89], v[78:81], v[20:23]
	v_mfma_f32_16x16x32_bf16 v[16:19], v[86:89], v[64:67], v[16:19]
	v_mfma_f32_16x16x32_bf16 v[12:15], v[82:85], v[94:97], v[12:15]
	v_mfma_f32_16x16x32_bf16 v[8:11], v[82:85], v[90:93], v[8:11]
	v_mfma_f32_16x16x32_bf16 v[4:7], v[82:85], v[78:81], v[4:7]
	v_mfma_f32_16x16x32_bf16 v[0:3], v[82:85], v[64:67], v[0:3]
	s_movk_i32 s4, 0x2400
	v_max_f32_e32 v60, v60, v60
	v_max_f32_e32 v56, v56, v56
	v_max_f32_e32 v52, v52, v52
	v_max_f32_e32 v48, v48, v48
	v_max_f32_e32 v44, v44, v44
	v_max_f32_e32 v40, v40, v40
	v_max_f32_e32 v36, v36, v36
	v_max_f32_e32 v32, v32, v32
	v_max_f32_e32 v28, v28, v28
	v_max_f32_e32 v24, v24, v24
	v_max_f32_e32 v20, v20, v20
	v_max_f32_e32 v16, v16, v16
	v_max_f32_e32 v12, v12, v12
	v_max_f32_e32 v8, v8, v8
	v_max_f32_e32 v4, v4, v4
	v_max_f32_e32 v0, v0, v0
	v_mul_lo_u32 v64, v72, s4
	v_max_f32_e32 v60, 0, v60
	v_max_f32_e32 v61, v61, v61
	v_max_f32_e32 v56, 0, v56
	v_max_f32_e32 v57, v57, v57
	v_max_f32_e32 v52, 0, v52
	v_max_f32_e32 v53, v53, v53
	v_max_f32_e32 v48, 0, v48
	v_max_f32_e32 v49, v49, v49
	v_max_f32_e32 v44, 0, v44
	v_max_f32_e32 v45, v45, v45
	v_max_f32_e32 v40, 0, v40
	v_max_f32_e32 v41, v41, v41
	v_max_f32_e32 v36, 0, v36
	v_max_f32_e32 v37, v37, v37
	v_max_f32_e32 v32, 0, v32
	v_max_f32_e32 v33, v33, v33
	v_max_f32_e32 v28, 0, v28
	v_max_f32_e32 v29, v29, v29
	v_max_f32_e32 v24, 0, v24
	v_max_f32_e32 v25, v25, v25
	v_max_f32_e32 v20, 0, v20
	v_max_f32_e32 v21, v21, v21
	v_max_f32_e32 v16, 0, v16
	v_max_f32_e32 v17, v17, v17
	v_max_f32_e32 v12, 0, v12
	v_max_f32_e32 v13, v13, v13
	v_max_f32_e32 v8, 0, v8
	v_max_f32_e32 v9, v9, v9
	v_max_f32_e32 v4, 0, v4
	v_max_f32_e32 v5, v5, v5
	v_max_f32_e32 v0, 0, v0
	v_max_f32_e32 v1, v1, v1
	v_lshl_or_b32 v65, v73, 1, v64
	v_mul_f32_e32 v60, v60, v60
	v_max_f32_e32 v61, 0, v61
	v_max_f32_e32 v62, v62, v62
	s_movk_i32 s4, 0x240
	v_mul_f32_e32 v56, v56, v56
	v_max_f32_e32 v57, 0, v57
	v_max_f32_e32 v58, v58, v58
	v_mul_f32_e32 v52, v52, v52
	v_max_f32_e32 v53, 0, v53
	v_max_f32_e32 v54, v54, v54
	v_mul_f32_e32 v48, v48, v48
	v_max_f32_e32 v49, 0, v49
	v_max_f32_e32 v50, v50, v50
	v_mul_f32_e32 v44, v44, v44
	v_max_f32_e32 v45, 0, v45
	v_max_f32_e32 v46, v46, v46
	v_mul_f32_e32 v40, v40, v40
	v_max_f32_e32 v41, 0, v41
	v_max_f32_e32 v42, v42, v42
	v_mul_f32_e32 v36, v36, v36
	v_max_f32_e32 v37, 0, v37
	v_max_f32_e32 v38, v38, v38
	v_mul_f32_e32 v32, v32, v32
	v_max_f32_e32 v33, 0, v33
	v_max_f32_e32 v34, v34, v34
	v_mul_f32_e32 v28, v28, v28
	v_max_f32_e32 v29, 0, v29
	v_max_f32_e32 v30, v30, v30
	v_mul_f32_e32 v24, v24, v24
	v_max_f32_e32 v25, 0, v25
	v_max_f32_e32 v26, v26, v26
	v_mul_f32_e32 v20, v20, v20
	v_max_f32_e32 v21, 0, v21
	v_max_f32_e32 v22, v22, v22
	v_mul_f32_e32 v16, v16, v16
	v_max_f32_e32 v17, 0, v17
	v_max_f32_e32 v18, v18, v18
	v_mul_f32_e32 v12, v12, v12
	v_max_f32_e32 v13, 0, v13
	v_max_f32_e32 v14, v14, v14
	v_mul_f32_e32 v8, v8, v8
	v_max_f32_e32 v9, 0, v9
	v_max_f32_e32 v10, v10, v10
	v_mul_f32_e32 v4, v4, v4
	v_max_f32_e32 v5, 0, v5
	v_max_f32_e32 v6, v6, v6
	v_mul_f32_e32 v0, v0, v0
	v_max_f32_e32 v1, 0, v1
	v_max_f32_e32 v2, v2, v2
	v_mul_f32_e32 v61, v61, v61
	v_max_f32_e32 v62, 0, v62
	v_max_f32_e32 v63, v63, v63
	v_cvt_pk_bf16_f32 v60, v60, s0
	v_mad_u32_u24 v65, v71, s4, v65
	v_mul_f32_e32 v57, v57, v57
	v_max_f32_e32 v58, 0, v58
	v_max_f32_e32 v59, v59, v59
	v_cvt_pk_bf16_f32 v56, v56, s0
	v_mul_f32_e32 v53, v53, v53
	v_max_f32_e32 v54, 0, v54
	v_max_f32_e32 v55, v55, v55
	v_cvt_pk_bf16_f32 v52, v52, s0
	v_mul_f32_e32 v49, v49, v49
	v_max_f32_e32 v50, 0, v50
	v_max_f32_e32 v51, v51, v51
	v_cvt_pk_bf16_f32 v48, v48, s0
	v_mul_f32_e32 v45, v45, v45
	v_max_f32_e32 v46, 0, v46
	v_max_f32_e32 v47, v47, v47
	v_cvt_pk_bf16_f32 v44, v44, s0
	v_mul_f32_e32 v41, v41, v41
	v_max_f32_e32 v42, 0, v42
	v_max_f32_e32 v43, v43, v43
	v_cvt_pk_bf16_f32 v40, v40, s0
	v_mul_f32_e32 v37, v37, v37
	v_max_f32_e32 v38, 0, v38
	v_max_f32_e32 v39, v39, v39
	v_cvt_pk_bf16_f32 v36, v36, s0
	v_mul_f32_e32 v33, v33, v33
	v_max_f32_e32 v34, 0, v34
	v_max_f32_e32 v35, v35, v35
	v_cvt_pk_bf16_f32 v32, v32, s0
	v_mul_f32_e32 v29, v29, v29
	v_max_f32_e32 v30, 0, v30
	v_max_f32_e32 v31, v31, v31
	v_cvt_pk_bf16_f32 v28, v28, s0
	v_mul_f32_e32 v25, v25, v25
	v_max_f32_e32 v26, 0, v26
	v_max_f32_e32 v27, v27, v27
	v_cvt_pk_bf16_f32 v24, v24, s0
	v_mul_f32_e32 v21, v21, v21
	v_max_f32_e32 v22, 0, v22
	v_max_f32_e32 v23, v23, v23
	v_cvt_pk_bf16_f32 v20, v20, s0
	v_mul_f32_e32 v17, v17, v17
	v_max_f32_e32 v18, 0, v18
	v_max_f32_e32 v19, v19, v19
	v_cvt_pk_bf16_f32 v16, v16, s0
	v_mul_f32_e32 v13, v13, v13
	v_max_f32_e32 v14, 0, v14
	v_max_f32_e32 v15, v15, v15
	v_cvt_pk_bf16_f32 v12, v12, s0
	v_mul_f32_e32 v9, v9, v9
	v_max_f32_e32 v10, 0, v10
	v_max_f32_e32 v11, v11, v11
	v_cvt_pk_bf16_f32 v8, v8, s0
	v_mul_f32_e32 v5, v5, v5
	v_max_f32_e32 v6, 0, v6
	v_max_f32_e32 v7, v7, v7
	v_cvt_pk_bf16_f32 v4, v4, s0
	v_mul_f32_e32 v1, v1, v1
	v_max_f32_e32 v2, 0, v2
	v_max_f32_e32 v3, v3, v3
	v_cvt_pk_bf16_f32 v0, v0, s0
	s_waitcnt vmcnt(0)
	s_barrier
	v_mul_f32_e32 v62, v62, v62
	v_max_f32_e32 v63, 0, v63
	ds_write_b16 v65, v60
	v_cvt_pk_bf16_f32 v60, v61, s0
	v_mul_f32_e32 v58, v58, v58
	v_max_f32_e32 v59, 0, v59
	ds_write_b16 v65, v56 offset:32
	v_cvt_pk_bf16_f32 v56, v57, s0
	v_mul_f32_e32 v54, v54, v54
	v_max_f32_e32 v55, 0, v55
	ds_write_b16 v65, v52 offset:64
	v_cvt_pk_bf16_f32 v52, v53, s0
	v_mul_f32_e32 v50, v50, v50
	v_max_f32_e32 v51, 0, v51
	ds_write_b16 v65, v48 offset:96
	v_cvt_pk_bf16_f32 v48, v49, s0
	v_mul_f32_e32 v46, v46, v46
	v_max_f32_e32 v47, 0, v47
	ds_write_b16 v65, v44 offset:2304
	v_cvt_pk_bf16_f32 v44, v45, s0
	v_mul_f32_e32 v42, v42, v42
	v_max_f32_e32 v43, 0, v43
	ds_write_b16 v65, v40 offset:2336
	v_cvt_pk_bf16_f32 v40, v41, s0
	v_mul_f32_e32 v38, v38, v38
	v_max_f32_e32 v39, 0, v39
	ds_write_b16 v65, v36 offset:2368
	v_cvt_pk_bf16_f32 v36, v37, s0
	v_mul_f32_e32 v34, v34, v34
	v_max_f32_e32 v35, 0, v35
	ds_write_b16 v65, v32 offset:2400
	v_cvt_pk_bf16_f32 v32, v33, s0
	v_mul_f32_e32 v30, v30, v30
	v_max_f32_e32 v31, 0, v31
	ds_write_b16 v65, v28 offset:4608
	v_cvt_pk_bf16_f32 v28, v29, s0
	v_mul_f32_e32 v26, v26, v26
	v_max_f32_e32 v27, 0, v27
	ds_write_b16 v65, v24 offset:4640
	v_cvt_pk_bf16_f32 v24, v25, s0
	v_mul_f32_e32 v22, v22, v22
	v_max_f32_e32 v23, 0, v23
	ds_write_b16 v65, v20 offset:4672
	v_cvt_pk_bf16_f32 v20, v21, s0
	v_mul_f32_e32 v18, v18, v18
	v_max_f32_e32 v19, 0, v19
	ds_write_b16 v65, v16 offset:4704
	v_cvt_pk_bf16_f32 v16, v17, s0
	v_mul_f32_e32 v14, v14, v14
	v_max_f32_e32 v15, 0, v15
	ds_write_b16 v65, v12 offset:6912
	v_cvt_pk_bf16_f32 v12, v13, s0
	v_mul_f32_e32 v10, v10, v10
	v_max_f32_e32 v11, 0, v11
	ds_write_b16 v65, v8 offset:6944
	v_cvt_pk_bf16_f32 v8, v9, s0
	v_mul_f32_e32 v6, v6, v6
	v_max_f32_e32 v7, 0, v7
	ds_write_b16 v65, v4 offset:6976
	v_cvt_pk_bf16_f32 v4, v5, s0
	v_mul_f32_e32 v2, v2, v2
	v_max_f32_e32 v3, 0, v3
	ds_write_b16 v65, v0 offset:7008
	v_cvt_pk_bf16_f32 v0, v1, s0
	v_mul_f32_e32 v63, v63, v63
	ds_write_b16 v65, v60 offset:144
	v_cvt_pk_bf16_f32 v60, v62, s0
	v_mul_f32_e32 v59, v59, v59
	ds_write_b16 v65, v56 offset:176
	v_cvt_pk_bf16_f32 v56, v58, s0
	v_mul_f32_e32 v55, v55, v55
	ds_write_b16 v65, v52 offset:208
	v_cvt_pk_bf16_f32 v52, v54, s0
	v_mul_f32_e32 v51, v51, v51
	ds_write_b16 v65, v48 offset:240
	v_cvt_pk_bf16_f32 v48, v50, s0
	v_mul_f32_e32 v47, v47, v47
	ds_write_b16 v65, v44 offset:2448
	v_cvt_pk_bf16_f32 v44, v46, s0
	v_mul_f32_e32 v43, v43, v43
	ds_write_b16 v65, v40 offset:2480
	v_cvt_pk_bf16_f32 v40, v42, s0
	v_mul_f32_e32 v39, v39, v39
	ds_write_b16 v65, v36 offset:2512
	v_cvt_pk_bf16_f32 v36, v38, s0
	v_mul_f32_e32 v35, v35, v35
	ds_write_b16 v65, v32 offset:2544
	v_cvt_pk_bf16_f32 v32, v34, s0
	v_mul_f32_e32 v31, v31, v31
	ds_write_b16 v65, v28 offset:4752
	v_cvt_pk_bf16_f32 v28, v30, s0
	v_mul_f32_e32 v27, v27, v27
	ds_write_b16 v65, v24 offset:4784
	v_cvt_pk_bf16_f32 v24, v26, s0
	v_mul_f32_e32 v23, v23, v23
	ds_write_b16 v65, v20 offset:4816
	v_cvt_pk_bf16_f32 v20, v22, s0
	v_mul_f32_e32 v19, v19, v19
	ds_write_b16 v65, v16 offset:4848
	v_cvt_pk_bf16_f32 v16, v18, s0
	v_mul_f32_e32 v15, v15, v15
	ds_write_b16 v65, v12 offset:7056
	v_cvt_pk_bf16_f32 v12, v14, s0
	v_mul_f32_e32 v11, v11, v11
	ds_write_b16 v65, v8 offset:7088
	v_cvt_pk_bf16_f32 v8, v10, s0
	v_mul_f32_e32 v7, v7, v7
	ds_write_b16 v65, v4 offset:7120
	v_cvt_pk_bf16_f32 v4, v6, s0
	v_mul_f32_e32 v3, v3, v3
	ds_write_b16 v65, v0 offset:7152
	v_cvt_pk_bf16_f32 v0, v2, s0
	v_add_u32_e32 v5, s1, v70
	s_ashr_i32 s1, s0, 31
	v_readlane_b32 s36, v246, 25
	ds_write_b16 v65, v60 offset:288
	v_cvt_pk_bf16_f32 v60, v63, s0
	ds_write_b16 v65, v56 offset:320
	v_cvt_pk_bf16_f32 v56, v59, s0
	ds_write_b16 v65, v52 offset:352
	v_cvt_pk_bf16_f32 v52, v55, s0
	ds_write_b16 v65, v48 offset:384
	v_cvt_pk_bf16_f32 v48, v51, s0
	ds_write_b16 v65, v44 offset:2592
	v_cvt_pk_bf16_f32 v44, v47, s0
	ds_write_b16 v65, v40 offset:2624
	v_cvt_pk_bf16_f32 v40, v43, s0
	ds_write_b16 v65, v36 offset:2656
	v_cvt_pk_bf16_f32 v36, v39, s0
	ds_write_b16 v65, v32 offset:2688
	v_cvt_pk_bf16_f32 v32, v35, s0
	ds_write_b16 v65, v28 offset:4896
	v_cvt_pk_bf16_f32 v28, v31, s0
	ds_write_b16 v65, v24 offset:4928
	v_cvt_pk_bf16_f32 v24, v27, s0
	ds_write_b16 v65, v20 offset:4960
	v_cvt_pk_bf16_f32 v20, v23, s0
	ds_write_b16 v65, v16 offset:4992
	v_cvt_pk_bf16_f32 v16, v19, s0
	ds_write_b16 v65, v12 offset:7200
	v_cvt_pk_bf16_f32 v12, v15, s0
	ds_write_b16 v65, v8 offset:7232
	v_cvt_pk_bf16_f32 v8, v11, s0
	ds_write_b16 v65, v4 offset:7264
	v_cvt_pk_bf16_f32 v4, v7, s0
	ds_write_b16 v65, v0 offset:7296
	v_cvt_pk_bf16_f32 v0, v3, s0
	s_lshl_b64 s[0:1], s[0:1], 1
	v_readlane_b32 s38, v246, 27
	ds_write_b16 v65, v0 offset:7440
	v_lshlrev_b32_e32 v0, 4, v69
	v_readlane_b32 s39, v246, 28
	s_add_u32 s0, s38, s0
	v_and_b32_e32 v0, 0x70, v0
	s_addc_u32 s1, s39, s1
	v_lshlrev_b32_e32 v136, 1, v134
	ds_write_b16 v65, v4 offset:7408
	v_or_b32_e32 v4, v64, v0
	v_lshl_add_u64 v[2:3], s[0:1], 0, v[136:137]
	s_movk_i32 s0, 0x90
	ds_write_b16 v65, v60 offset:432
	ds_write_b16 v65, v56 offset:464
	ds_write_b16 v65, v52 offset:496
	ds_write_b16 v65, v48 offset:528
	ds_write_b16 v65, v44 offset:2736
	ds_write_b16 v65, v40 offset:2768
	ds_write_b16 v65, v36 offset:2800
	ds_write_b16 v65, v32 offset:2832
	ds_write_b16 v65, v28 offset:5040
	ds_write_b16 v65, v24 offset:5072
	ds_write_b16 v65, v20 offset:5104
	ds_write_b16 v65, v16 offset:5136
	ds_write_b16 v65, v12 offset:7344
	ds_write_b16 v65, v8 offset:7376
	v_mov_b32_e32 v1, v137
	v_mad_u32_u24 v12, v68, s0, v4
	v_lshl_add_u64 v[8:9], v[2:3], 0, v[0:1]
	ds_read_b128 v[0:3], v12
	v_or_b32_e32 v13, v5, v68
	ds_read_b128 v[4:7], v12 offset:1152
	s_movk_i32 s4, 0x2080
	v_mad_i64_i32 v[10:11], s[0:1], v13, s4, v[8:9]
	s_waitcnt lgkmcnt(1)
	global_store_dwordx4 v[10:11], v[0:3], off
	s_add_i32 s6, s6, 1
	s_movk_i32 s36, 0x880
	v_or_b32_e32 v0, 8, v13
	v_mad_i64_i32 v[0:1], s[0:1], v0, s4, v[8:9]
	s_waitcnt lgkmcnt(0)
	global_store_dwordx4 v[0:1], v[4:7], off
	ds_read_b128 v[0:3], v12 offset:2304
	v_readlane_b32 s37, v246, 26
	v_or_b32_e32 v4, 16, v13
	v_mad_i64_i32 v[10:11], s[0:1], v4, s4, v[8:9]
	ds_read_b128 v[4:7], v12 offset:3456
	s_waitcnt lgkmcnt(1)
	global_store_dwordx4 v[10:11], v[0:3], off
	v_readlane_b32 s40, v246, 29
	v_readlane_b32 s41, v246, 30
	v_or_b32_e32 v0, 24, v13
	v_mad_i64_i32 v[0:1], s[0:1], v0, s4, v[8:9]
	s_waitcnt lgkmcnt(0)
	global_store_dwordx4 v[0:1], v[4:7], off
	ds_read_b128 v[0:3], v12 offset:4608
	v_readlane_b32 s42, v246, 31
	v_or_b32_e32 v4, 32, v13
	v_mad_i64_i32 v[10:11], s[0:1], v4, s4, v[8:9]
	ds_read_b128 v[4:7], v12 offset:5760
	s_waitcnt lgkmcnt(1)
	global_store_dwordx4 v[10:11], v[0:3], off
	v_readlane_b32 s43, v246, 32
	v_readlane_b32 s44, v246, 33
	v_or_b32_e32 v0, 40, v13
	v_mad_i64_i32 v[0:1], s[0:1], v0, s4, v[8:9]
	s_waitcnt lgkmcnt(0)
	global_store_dwordx4 v[0:1], v[4:7], off
	ds_read_b128 v[0:3], v12 offset:6912
	v_readlane_b32 s45, v246, 34
	v_or_b32_e32 v4, 48, v13
	v_mad_i64_i32 v[10:11], s[0:1], v4, s4, v[8:9]
	ds_read_b128 v[4:7], v12 offset:8064
	s_waitcnt lgkmcnt(1)
	global_store_dwordx4 v[10:11], v[0:3], off
	v_readlane_b32 s46, v246, 35
	v_readlane_b32 s47, v246, 36
	v_or_b32_e32 v0, 56, v13
	v_mad_i64_i32 v[0:1], s[0:1], v0, s4, v[8:9]
	s_mov_b64 s[4:5], 0
	v_readlane_b32 s48, v246, 37
	v_readlane_b32 s49, v246, 38
	v_readlane_b32 s50, v246, 39
	v_readlane_b32 s51, v246, 40
	s_waitcnt lgkmcnt(0)
	global_store_dwordx4 v[0:1], v[4:7], off
	s_barrier
	s_branch .LBB0_141

.LBB0_170:
	s_mov_b64 s[6:7], -1
	s_and_b64 vcc, exec, s[4:5]
	s_cbranch_vccz .LBB0_162
	v_mov_b32_e32 v71, v139
	v_readlane_b32 s40, v246, 9
	v_ashrrev_i32_e32 v68, 6, v71
	s_waitcnt vmcnt(48)
	v_lshlrev_b32_e32 v6, 3, v68
	v_bfe_u32 v70, v71, 3, 3
	s_lshl_b32 s5, s9, 7
	v_or_b32_e32 v2, v6, v70
	v_readlane_b32 s54, v246, 23
	v_readlane_b32 s55, v246, 24
	v_lshrrev_b32_e32 v7, 1, v2
	v_add_u32_e32 v4, s5, v2
	v_readlane_b32 s41, v246, 10
	v_readlane_b32 s42, v246, 11
	v_readlane_b32 s43, v246, 12
	v_readlane_b32 s44, v246, 13
	v_readlane_b32 s45, v246, 14
	v_readlane_b32 s46, v246, 15
	v_readlane_b32 s47, v246, 16
	v_readlane_b32 s48, v246, 17
	v_readlane_b32 s49, v246, 18
	v_readlane_b32 s50, v246, 19
	v_readlane_b32 s51, v246, 20
	v_mov_b64_e32 v[0:1], s[54:55]
	v_xor_b32_e32 v3, v7, v71
	v_mad_i64_i32 v[0:1], s[6:7], v4, s36, v[0:1]
	v_readlane_b32 s36, v247, 57
	s_lshl_b32 s4, s10, 7
	v_lshlrev_b32_e32 v3, 4, v3
	v_readlane_b32 s50, v246, 7
	v_readlane_b32 s51, v246, 8
	v_and_b32_e32 v136, 0x70, v3
	v_add_u32_e32 v4, s4, v2
	s_movk_i32 s9, 0x880
	v_mov_b64_e32 v[2:3], s[50:51]
	v_mad_i64_i32 v[2:3], s[6:7], v4, s9, v[2:3]
	v_lshlrev_b32_e32 v72, 10, v68
	v_add_u32_e32 v4, 0x4000, v72
	v_readfirstlane_b32 s6, v72
	v_lshl_add_u64 v[0:1], v[0:1], 0, v[136:137]
	s_mov_b32 m0, s6
	v_readfirstlane_b32 s6, v4
	v_add_u32_e32 v9, 0x1000, v72
	v_lshl_add_u64 v[2:3], v[2:3], 0, v[136:137]
	global_load_lds_dwordx4 v[0:1], off
	s_mov_b32 m0, s6
	s_mov_b64 s[10:11], 0x11000
	v_readfirstlane_b32 s6, v9
	v_add_u32_e32 v9, 0x5000, v72
	global_load_lds_dwordx4 v[2:3], off
	v_lshl_add_u64 v[4:5], v[0:1], 0, s[10:11]
	s_mov_b32 m0, s6
	v_readfirstlane_b32 s6, v9
	v_add_u32_e32 v9, 0x2000, v72
	global_load_lds_dwordx4 v[4:5], off
	v_lshl_add_u64 v[4:5], v[2:3], 0, s[10:11]
	s_mov_b32 m0, s6
	s_mov_b64 s[10:11], 0x22000
	v_readfirstlane_b32 s6, v9
	v_add_u32_e32 v9, 0x6000, v72
	global_load_lds_dwordx4 v[4:5], off
	v_lshl_add_u64 v[4:5], v[0:1], 0, s[10:11]
	s_mov_b32 m0, s6
	v_readfirstlane_b32 s6, v9
	global_load_lds_dwordx4 v[4:5], off
	v_lshl_add_u64 v[4:5], v[2:3], 0, s[10:11]
	s_mov_b32 m0, s6
	s_mov_b64 s[10:11], 0x33000
	global_load_lds_dwordx4 v[4:5], off
	v_add_u32_e32 v4, 0x3000, v72
	v_lshl_add_u64 v[0:1], v[0:1], 0, s[10:11]
	v_readfirstlane_b32 s6, v4
	s_mov_b32 m0, s6
	v_bfe_u32 v75, v71, 4, 2
	global_load_lds_dwordx4 v[0:1], off
	v_lshl_add_u64 v[0:1], v[2:3], 0, s[10:11]
	v_add_u32_e32 v2, 0x7000, v72
	v_and_b32_e32 v76, 15, v71
	v_readfirstlane_b32 s6, v2
	s_mov_b32 m0, s6
	v_lshrrev_b32_e32 v8, 1, v71
	global_load_lds_dwordx4 v[0:1], off
	v_ashrrev_i32_e32 v1, 1, v71
	v_bfe_u32 v0, v71, 1, 3
	v_and_b32_e32 v69, 0xffffffc0, v1
	v_or_b32_e32 v1, v69, v76
	v_bitop3_b32 v0, v75, v0, 4 bitop3:0x36
	v_lshlrev_b32_e32 v73, 7, v1
	v_bitop3_b32 v1, v75, v8, 7 bitop3:0x78
	v_lshlrev_b32_e32 v77, 4, v0
	v_or_b32_e32 v0, s5, v70
	v_lshlrev_b32_e32 v78, 4, v1
	v_lshlrev_b32_e32 v1, 7, v71
	v_add_u32_e32 v0, v0, v6
	v_bitop3_b32 v2, v7, 7, v71 bitop3:0x48
	v_and_b32_e32 v74, 0x2780, v1
	v_mad_i64_i32 v[0:1], s[6:7], v0, s9, 0
	v_lshlrev_b32_e32 v2, 4, v2
	v_or_b32_e32 v0, v0, v2
	v_lshl_add_u64 v[64:65], s[54:55], 0, v[0:1]
	v_or_b32_e32 v0, s4, v70
	v_add_u32_e32 v0, v0, v6
	v_mad_i64_i32 v[0:1], s[6:7], v0, s9, 0
	s_waitcnt vmcnt(0)
	v_or_b32_e32 v0, v0, v2
	v_lshl_add_u64 v[66:67], s[50:51], 0, v[0:1]
	v_mov_b32_e32 v0, 0
	s_mov_b64 s[6:7], 0
	s_mov_b32 s9, 0
	v_mov_b32_e32 v1, v0
	v_mov_b32_e32 v2, v0
	v_mov_b32_e32 v3, v0
	v_mov_b32_e32 v4, v0
	v_mov_b32_e32 v5, v0
	v_mov_b32_e32 v6, v0
	v_mov_b32_e32 v7, v0
	v_mov_b32_e32 v8, v0
	v_mov_b32_e32 v9, v0
	v_mov_b32_e32 v10, v0
	v_mov_b32_e32 v11, v0
	s_waitcnt vmcnt(0)
	v_mov_b32_e32 v12, v0
	v_mov_b32_e32 v13, v0
	v_mov_b32_e32 v14, v0
	v_mov_b32_e32 v15, v0
	v_mov_b32_e32 v16, v0
	v_mov_b32_e32 v17, v0
	v_mov_b32_e32 v18, v0
	v_mov_b32_e32 v19, v0
	v_mov_b32_e32 v20, v0
	v_mov_b32_e32 v21, v0
	v_mov_b32_e32 v22, v0
	v_mov_b32_e32 v23, v0
	v_mov_b32_e32 v24, v0
	v_mov_b32_e32 v25, v0
	v_mov_b32_e32 v26, v0
	v_mov_b32_e32 v27, v0
	v_mov_b32_e32 v28, v0
	v_mov_b32_e32 v29, v0
	v_mov_b32_e32 v30, v0
	v_mov_b32_e32 v31, v0
	v_mov_b32_e32 v32, v0
	v_mov_b32_e32 v33, v0
	v_mov_b32_e32 v34, v0
	v_mov_b32_e32 v35, v0
	v_mov_b32_e32 v36, v0
	v_mov_b32_e32 v37, v0
	v_mov_b32_e32 v38, v0
	v_mov_b32_e32 v39, v0
	v_mov_b32_e32 v40, v0
	v_mov_b32_e32 v41, v0
	v_mov_b32_e32 v42, v0
	v_mov_b32_e32 v43, v0
	v_mov_b32_e32 v44, v0
	v_mov_b32_e32 v45, v0
	v_mov_b32_e32 v46, v0
	v_mov_b32_e32 v47, v0
	v_mov_b32_e32 v48, v0
	v_mov_b32_e32 v49, v0
	v_mov_b32_e32 v50, v0
	v_mov_b32_e32 v51, v0
	v_mov_b32_e32 v52, v0
	v_mov_b32_e32 v53, v0
	v_mov_b32_e32 v54, v0
	v_mov_b32_e32 v55, v0
	v_mov_b32_e32 v56, v0
	v_mov_b32_e32 v57, v0
	v_mov_b32_e32 v58, v0
	v_mov_b32_e32 v59, v0
	v_mov_b32_e32 v60, v0
	v_mov_b32_e32 v61, v0
	v_mov_b32_e32 v62, v0
	v_mov_b32_e32 v63, v0
	s_mov_b64 s[12:13], 0x11080
	s_mov_b64 s[14:15], 0x33080
	s_mov_b64 s[16:17], 0x22080
	v_readlane_b32 s52, v246, 21
	v_readlane_b32 s53, v246, 22
	v_readlane_b32 s37, v247, 58
	v_readlane_b32 s38, v247, 59
	v_readlane_b32 s39, v247, 60
	v_readlane_b32 s40, v247, 61
	v_readlane_b32 s41, v247, 62
	v_readlane_b32 s42, v247, 63
	v_readlane_b32 s43, v246, 0
	v_readlane_b32 s44, v246, 1
	v_readlane_b32 s45, v246, 2
	v_readlane_b32 s46, v246, 3
	v_readlane_b32 s47, v246, 4
	v_readlane_b32 s48, v246, 5
	v_readlane_b32 s49, v246, 6
	s_waitcnt vmcnt(0) lgkmcnt(0)
	s_barrier
	s_bitcmp1_b32 s68, 8
	s_cbranch_scc0 gp172_skip
	s_setprio 1
gp172_skip:
.LBB0_172:
	s_and_b32 s10, s9, 0x8000
	s_xor_b32 s11, s10, 0x8000
	v_add_u32_e32 v79, s11, v72
	v_lshl_add_u64 v[80:81], v[64:65], 0, s[6:7]
	v_readfirstlane_b32 s11, v79
	v_lshl_add_u64 v[82:83], v[80:81], 0, s[28:29]
	s_mov_b32 m0, s11
	v_lshl_add_u64 v[84:85], v[66:67], 0, s[6:7]
	global_load_lds_dwordx4 v[82:83], off
	v_add_u32_e32 v82, 0x4000, v79
	v_lshl_add_u64 v[86:87], v[84:85], 0, s[28:29]
	v_readfirstlane_b32 s11, v82
	s_mov_b32 m0, s11
	v_lshl_add_u64 v[82:83], v[80:81], 0, s[12:13]
	global_load_lds_dwordx4 v[86:87], off
	v_add_u32_e32 v86, 0x1000, v79
	s_nop 0
	v_readfirstlane_b32 s11, v86
	v_add_u32_e32 v86, 0x5000, v79
	s_mov_b32 m0, s11
	v_readfirstlane_b32 s11, v86
	v_add_u32_e32 v86, 0x2000, v79
	global_load_lds_dwordx4 v[82:83], off
	v_lshl_add_u64 v[82:83], v[84:85], 0, s[12:13]
	s_mov_b32 m0, s11
	v_readfirstlane_b32 s11, v86
	v_add_u32_e32 v86, 0x6000, v79
	global_load_lds_dwordx4 v[82:83], off
	v_lshl_add_u64 v[82:83], v[80:81], 0, s[16:17]
	s_mov_b32 m0, s11
	v_readfirstlane_b32 s11, v86
	global_load_lds_dwordx4 v[82:83], off
	v_lshl_add_u64 v[82:83], v[84:85], 0, s[16:17]
	s_mov_b32 m0, s11
	v_lshl_add_u64 v[80:81], v[80:81], 0, s[14:15]
	global_load_lds_dwordx4 v[82:83], off
	v_add_u32_e32 v82, 0x3000, v79
	v_add_u32_e32 v79, 0x7000, v79
	v_readfirstlane_b32 s11, v82
	s_mov_b32 m0, s11
	v_readfirstlane_b32 s11, v79
	global_load_lds_dwordx4 v[80:81], off
	v_lshl_add_u64 v[80:81], v[84:85], 0, s[14:15]
	s_mov_b32 m0, s11
	v_or_b32_e32 v79, s10, v78
	global_load_lds_dwordx4 v[80:81], off
	v_add_u32_e32 v100, v79, v73
	v_add_u32_e32 v79, v79, v74
	ds_read_b128 v[80:83], v100
	ds_read_b128 v[84:87], v100 offset:2048
	ds_read_b128 v[88:91], v79 offset:16384
	ds_read_b128 v[92:95], v79 offset:18432
	ds_read_b128 v[96:99], v100 offset:4096
	ds_read_b128 v[100:103], v100 offset:6144
	ds_read_b128 v[104:107], v79 offset:20480
	ds_read_b128 v[108:111], v79 offset:22528
	v_or_b32_e32 v79, s10, v77
	v_add_u32_e32 v132, v79, v73
	v_add_u32_e32 v79, v79, v74
	ds_read_b128 v[112:115], v132
	ds_read_b128 v[116:119], v132 offset:2048
	ds_read_b128 v[120:123], v79 offset:16384
	ds_read_b128 v[124:127], v79 offset:18432
	ds_read_b128 v[128:131], v132 offset:4096
	ds_read_b128 v[132:135], v132 offset:6144
	ds_read_b128 v[146:149], v79 offset:20480
	ds_read_b128 v[150:153], v79 offset:22528
	s_waitcnt lgkmcnt(0)
	v_mfma_f32_16x16x32_bf16 v[60:63], v[80:83], v[88:91], v[60:63]
	v_mfma_f32_16x16x32_bf16 v[56:59], v[80:83], v[92:95], v[56:59]
	v_mfma_f32_16x16x32_bf16 v[52:55], v[80:83], v[104:107], v[52:55]
	v_mfma_f32_16x16x32_bf16 v[48:51], v[80:83], v[108:111], v[48:51]
	v_mfma_f32_16x16x32_bf16 v[44:47], v[84:87], v[88:91], v[44:47]
	v_mfma_f32_16x16x32_bf16 v[40:43], v[84:87], v[92:95], v[40:43]
	v_mfma_f32_16x16x32_bf16 v[36:39], v[84:87], v[104:107], v[36:39]
	v_mfma_f32_16x16x32_bf16 v[32:35], v[84:87], v[108:111], v[32:35]
	v_mfma_f32_16x16x32_bf16 v[28:31], v[96:99], v[88:91], v[28:31]
	v_mfma_f32_16x16x32_bf16 v[24:27], v[96:99], v[92:95], v[24:27]
	v_mfma_f32_16x16x32_bf16 v[20:23], v[96:99], v[104:107], v[20:23]
	v_mfma_f32_16x16x32_bf16 v[16:19], v[96:99], v[108:111], v[16:19]
	v_mfma_f32_16x16x32_bf16 v[12:15], v[100:103], v[88:91], v[12:15]
	v_mfma_f32_16x16x32_bf16 v[8:11], v[100:103], v[92:95], v[8:11]
	v_mfma_f32_16x16x32_bf16 v[4:7], v[100:103], v[104:107], v[4:7]
	v_mfma_f32_16x16x32_bf16 v[0:3], v[100:103], v[108:111], v[0:3]
	v_mfma_f32_16x16x32_bf16 v[60:63], v[112:115], v[120:123], v[60:63]
	v_mfma_f32_16x16x32_bf16 v[56:59], v[112:115], v[124:127], v[56:59]
	v_mfma_f32_16x16x32_bf16 v[52:55], v[112:115], v[146:149], v[52:55]
	v_mfma_f32_16x16x32_bf16 v[48:51], v[112:115], v[150:153], v[48:51]
	v_mfma_f32_16x16x32_bf16 v[44:47], v[116:119], v[120:123], v[44:47]
	v_mfma_f32_16x16x32_bf16 v[40:43], v[116:119], v[124:127], v[40:43]
	v_mfma_f32_16x16x32_bf16 v[36:39], v[116:119], v[146:149], v[36:39]
	v_mfma_f32_16x16x32_bf16 v[32:35], v[116:119], v[150:153], v[32:35]
	v_mfma_f32_16x16x32_bf16 v[28:31], v[128:131], v[120:123], v[28:31]
	v_mfma_f32_16x16x32_bf16 v[24:27], v[128:131], v[124:127], v[24:27]
	v_mfma_f32_16x16x32_bf16 v[20:23], v[128:131], v[146:149], v[20:23]
	v_mfma_f32_16x16x32_bf16 v[16:19], v[128:131], v[150:153], v[16:19]
	v_mfma_f32_16x16x32_bf16 v[12:15], v[132:135], v[120:123], v[12:15]
	v_mfma_f32_16x16x32_bf16 v[8:11], v[132:135], v[124:127], v[8:11]
	v_mfma_f32_16x16x32_bf16 v[4:7], v[132:135], v[146:149], v[4:7]
	v_mfma_f32_16x16x32_bf16 v[0:3], v[132:135], v[150:153], v[0:3]
	s_waitcnt vmcnt(0)
	s_add_u32 s6, s6, 0x80
	s_addc_u32 s7, s7, 0
	s_add_i32 s9, s9, 0x8000
	s_cmpk_eq_i32 s6, 0x780
	s_barrier
	s_cbranch_scc0 .LBB0_172
	s_setprio 0
	v_add_u32_e32 v72, v78, v73
	v_add_u32_e32 v102, v78, v74
	ds_read_b128 v[64:67], v72 offset:32768
	ds_read_b128 v[78:81], v72 offset:34816
	ds_read_b128 v[82:85], v102 offset:49152
	ds_read_b128 v[86:89], v102 offset:51200
	ds_read_b128 v[90:93], v72 offset:36864
	ds_read_b128 v[94:97], v72 offset:38912
	ds_read_b128 v[98:101], v102 offset:53248
	ds_read_b128 v[102:105], v102 offset:55296
	v_add_u32_e32 v72, v77, v73
	v_add_u32_e32 v73, v77, v74
	ds_read_b128 v[106:109], v72 offset:32768
	ds_read_b128 v[110:113], v72 offset:34816
	ds_read_b128 v[114:117], v73 offset:49152
	ds_read_b128 v[118:121], v73 offset:51200
	ds_read_b128 v[122:125], v72 offset:36864
	ds_read_b128 v[126:129], v72 offset:38912
	ds_read_b128 v[130:133], v73 offset:53248
	ds_read_b128 v[146:149], v73 offset:55296
	s_waitcnt lgkmcnt(13)
	v_mfma_f32_16x16x32_bf16 v[60:63], v[64:67], v[82:85], v[60:63]
	s_waitcnt lgkmcnt(12)
	v_mfma_f32_16x16x32_bf16 v[56:59], v[64:67], v[86:89], v[56:59]
	s_waitcnt lgkmcnt(9)
	v_mfma_f32_16x16x32_bf16 v[52:55], v[64:67], v[98:101], v[52:55]
	s_waitcnt lgkmcnt(8)
	v_mfma_f32_16x16x32_bf16 v[48:51], v[64:67], v[102:105], v[48:51]
	v_mfma_f32_16x16x32_bf16 v[44:47], v[78:81], v[82:85], v[44:47]
	v_mfma_f32_16x16x32_bf16 v[40:43], v[78:81], v[86:89], v[40:43]
	v_mfma_f32_16x16x32_bf16 v[36:39], v[78:81], v[98:101], v[36:39]
	v_mfma_f32_16x16x32_bf16 v[32:35], v[78:81], v[102:105], v[32:35]
	v_mfma_f32_16x16x32_bf16 v[28:31], v[90:93], v[82:85], v[28:31]
	v_mfma_f32_16x16x32_bf16 v[24:27], v[90:93], v[86:89], v[24:27]
	v_mfma_f32_16x16x32_bf16 v[20:23], v[90:93], v[98:101], v[20:23]
	v_mfma_f32_16x16x32_bf16 v[16:19], v[90:93], v[102:105], v[16:19]
	v_mfma_f32_16x16x32_bf16 v[12:15], v[94:97], v[82:85], v[12:15]
	v_mfma_f32_16x16x32_bf16 v[8:11], v[94:97], v[86:89], v[8:11]
	v_mfma_f32_16x16x32_bf16 v[4:7], v[94:97], v[98:101], v[4:7]
	v_mfma_f32_16x16x32_bf16 v[0:3], v[94:97], v[102:105], v[0:3]
	s_waitcnt lgkmcnt(5)
	v_mfma_f32_16x16x32_bf16 v[78:81], v[106:109], v[114:117], v[60:63]
	s_waitcnt lgkmcnt(4)
	v_mfma_f32_16x16x32_bf16 v[56:59], v[106:109], v[118:121], v[56:59]
	s_waitcnt lgkmcnt(1)
	v_mfma_f32_16x16x32_bf16 v[52:55], v[106:109], v[130:133], v[52:55]
	s_waitcnt lgkmcnt(0)
	v_mfma_f32_16x16x32_bf16 v[48:51], v[106:109], v[146:149], v[48:51]
	v_mfma_f32_16x16x32_bf16 v[44:47], v[110:113], v[114:117], v[44:47]
	v_mfma_f32_16x16x32_bf16 v[40:43], v[110:113], v[118:121], v[40:43]
	v_mfma_f32_16x16x32_bf16 v[36:39], v[110:113], v[130:133], v[36:39]
	v_mfma_f32_16x16x32_bf16 v[32:35], v[110:113], v[146:149], v[32:35]
	v_mfma_f32_16x16x32_bf16 v[28:31], v[122:125], v[114:117], v[28:31]
	v_mfma_f32_16x16x32_bf16 v[24:27], v[122:125], v[118:121], v[24:27]
	v_mfma_f32_16x16x32_bf16 v[20:23], v[122:125], v[130:133], v[20:23]
	v_mfma_f32_16x16x32_bf16 v[16:19], v[122:125], v[146:149], v[16:19]
	v_mfma_f32_16x16x32_bf16 v[12:15], v[126:129], v[114:117], v[12:15]
	v_mfma_f32_16x16x32_bf16 v[8:11], v[126:129], v[118:121], v[8:11]
	v_mfma_f32_16x16x32_bf16 v[4:7], v[126:129], v[130:133], v[4:7]
	v_mfma_f32_16x16x32_bf16 v[0:3], v[126:129], v[146:149], v[0:3]
	v_add_u32_e32 v72, s5, v69
	v_add_u32_e32 v61, 0xfffff000, v72
	s_movk_i32 s6, 0x2400
	v_lshl_or_b32 v60, v75, 2, v72
	v_lshrrev_b32_e32 v61, 12, v61
	s_movk_i32 s9, 0xfff
	v_mul_lo_u32 v74, v68, s6
	v_add_u32_e32 v61, 1, v61
	v_cmp_lt_i32_e32 vcc, s9, v60
	v_readlane_b32 s6, v245, 44
	v_readlane_b32 s7, v245, 45
	v_cndmask_b32_e32 v136, 0, v61, vcc
	v_lshl_add_u64 v[66:67], v[136:137], 0, s[0:1]
	v_mov_b64_e32 v[64:65], s[6:7]
	s_movk_i32 s5, 0x6000
	v_mad_u64_u32 v[68:69], s[6:7], v66, s5, v[64:65]
	v_or_b32_e32 v66, 1, v60
	v_mad_i32_i24 v69, v67, s5, v69
	v_ashrrev_i32_e32 v67, 31, v66
	v_lshlrev_b64 v[84:85], 12, v[66:67]
	v_or_b32_e32 v66, 2, v60
	v_and_b32_e32 v73, 64, v71
	v_ashrrev_i32_e32 v67, 31, v66
	v_or3_b32 v62, v76, s4, v73
	v_lshlrev_b64 v[86:87], 12, v[66:67]
	v_or_b32_e32 v66, 3, v60
	v_readlane_b32 s36, v247, 57
	v_ashrrev_i32_e32 v61, 31, v60
	v_ashrrev_i32_e32 v67, 31, v66
	v_ashrrev_i32_e32 v63, 31, v62
	v_readlane_b32 s46, v246, 3
	v_readlane_b32 s47, v246, 4
	v_lshlrev_b64 v[82:83], 12, v[60:61]
	v_lshlrev_b64 v[88:89], 12, v[66:67]
	v_lshlrev_b64 v[66:67], 2, v[62:63]
	v_lshl_add_u64 v[62:63], v[62:63], 1, s[46:47]
	v_lshl_add_u64 v[82:83], v[62:63], 0, v[82:83]
	s_waitcnt vmcnt(0)
	s_barrier
	global_load_ushort v202, v[82:83], off
	v_lshl_add_u64 v[68:69], v[68:69], 0, v[66:67]
	global_load_dword v203, v[68:69], off
	v_lshl_add_u64 v[84:85], v[62:63], 0, v[84:85]
	global_load_ushort v204, v[84:85], off
	s_movk_i32 s6, 0x240
	s_movk_i32 s36, 0x880
	v_readlane_b32 s37, v247, 58
	v_readlane_b32 s38, v247, 59
	v_readlane_b32 s39, v247, 60
	v_readlane_b32 s40, v247, 61
	v_readlane_b32 s41, v247, 62
	v_readlane_b32 s42, v247, 63
	v_readlane_b32 s43, v246, 0
	v_readlane_b32 s44, v246, 1
	v_readlane_b32 s45, v246, 2
	v_readlane_b32 s48, v246, 5
	v_readlane_b32 s49, v246, 6
	v_readlane_b32 s50, v246, 7
	v_readlane_b32 s51, v246, 8
	s_waitcnt vmcnt(2)
	v_lshlrev_b32_e32 v77, 16, v202
	v_mul_f32_e32 v77, 0x3fd744fd, v77
	s_waitcnt vmcnt(1)
	v_fmac_f32_e32 v77, v78, v203
	s_waitcnt vmcnt(0)
	v_lshlrev_b32_e32 v78, 16, v204
	v_mul_f32_e32 v90, 0x3fd744fd, v78
	v_fmac_f32_e32 v90, v79, v203
	v_lshl_add_u64 v[78:79], v[62:63], 0, v[86:87]
	global_load_ushort v205, v[78:79], off
	s_waitcnt vmcnt(0)
	v_lshlrev_b32_e32 v86, 16, v205
	v_mul_f32_e32 v91, 0x3fd744fd, v86
	v_lshl_add_u64 v[86:87], v[62:63], 0, v[88:89]
	global_load_ushort v206, v[86:87], off
	global_load_dword v207, v[68:69], off offset:64
	global_load_ushort v208, v[82:83], off offset:32
	global_load_ushort v209, v[84:85], off offset:32
	global_load_ushort v210, v[78:79], off offset:32
	global_load_ushort v211, v[86:87], off offset:32
	global_load_dword v212, v[68:69], off offset:128
	global_load_ushort v213, v[82:83], off offset:64
	global_load_ushort v214, v[84:85], off offset:64
	global_load_ushort v215, v[78:79], off offset:64
	global_load_ushort v216, v[86:87], off offset:64
	global_load_dword v217, v[68:69], off offset:192
	global_load_ushort v218, v[82:83], off offset:96
	global_load_ushort v219, v[84:85], off offset:96
	global_load_ushort v220, v[78:79], off offset:96
	global_load_ushort v221, v[86:87], off offset:96
	v_fmac_f32_e32 v91, v80, v203
	s_waitcnt vmcnt(15)
	v_lshlrev_b32_e32 v80, 16, v206
	v_mul_f32_e32 v80, 0x3fd744fd, v80
	v_fmac_f32_e32 v80, v81, v203
	v_lshl_or_b32 v61, v76, 1, v74
	v_mad_u32_u24 v61, v75, s6, v61
	v_cvt_pk_bf16_f32 v75, v90, s0
	ds_write_b16 v61, v75 offset:144
	v_cvt_pk_bf16_f32 v75, v91, s0
	v_cvt_pk_bf16_f32 v76, v77, s0
	ds_write_b16 v61, v75 offset:288
	v_cvt_pk_bf16_f32 v75, v80, s0
	ds_write_b16 v61, v76
	ds_write_b16 v61, v75 offset:432
	s_waitcnt vmcnt(13)
	v_lshlrev_b32_e32 v76, 16, v208
	v_mul_f32_e32 v76, 0x3fd744fd, v76
	v_fmac_f32_e32 v76, v56, v207
	s_waitcnt vmcnt(12)
	v_lshlrev_b32_e32 v56, 16, v209
	v_mul_f32_e32 v56, 0x3fd744fd, v56
	v_fmac_f32_e32 v56, v57, v207
	v_cvt_pk_bf16_f32 v56, v56, s0
	ds_write_b16 v61, v56 offset:176
	s_waitcnt vmcnt(11)
	v_lshlrev_b32_e32 v57, 16, v210
	v_mul_f32_e32 v57, 0x3fd744fd, v57
	v_fmac_f32_e32 v57, v58, v207
	v_cvt_pk_bf16_f32 v56, v57, s0
	ds_write_b16 v61, v56 offset:320
	s_waitcnt vmcnt(10)
	v_lshlrev_b32_e32 v58, 16, v211
	v_mul_f32_e32 v58, 0x3fd744fd, v58
	v_fmac_f32_e32 v58, v59, v207
	v_cvt_pk_bf16_f32 v59, v76, s0
	v_cvt_pk_bf16_f32 v56, v58, s0
	ds_write_b16 v61, v59 offset:32
	ds_write_b16 v61, v56 offset:464
	s_waitcnt vmcnt(8)
	v_lshlrev_b32_e32 v57, 16, v213
	v_mul_f32_e32 v57, 0x3fd744fd, v57
	v_fmac_f32_e32 v57, v52, v212
	s_waitcnt vmcnt(7)
	v_lshlrev_b32_e32 v52, 16, v214
	v_mul_f32_e32 v52, 0x3fd744fd, v52
	v_fmac_f32_e32 v52, v53, v212
	v_cvt_pk_bf16_f32 v52, v52, s0
	ds_write_b16 v61, v52 offset:208
	s_waitcnt vmcnt(6)
	v_lshlrev_b32_e32 v53, 16, v215
	v_mul_f32_e32 v53, 0x3fd744fd, v53
	v_fmac_f32_e32 v53, v54, v212
	v_cvt_pk_bf16_f32 v52, v53, s0
	ds_write_b16 v61, v52 offset:352
	s_waitcnt vmcnt(5)
	v_lshlrev_b32_e32 v54, 16, v216
	v_mul_f32_e32 v54, 0x3fd744fd, v54
	v_fmac_f32_e32 v54, v55, v212
	v_cvt_pk_bf16_f32 v55, v57, s0
	v_cvt_pk_bf16_f32 v52, v54, s0
	ds_write_b16 v61, v55 offset:64
	ds_write_b16 v61, v52 offset:496
	v_or_b32_e32 v54, 18, v60
	v_ashrrev_i32_e32 v55, 31, v54
	v_lshlrev_b64 v[56:57], 12, v[54:55]
	v_or_b32_e32 v54, 19, v60
	v_ashrrev_i32_e32 v55, 31, v54
	v_lshlrev_b64 v[58:59], 12, v[54:55]
	s_waitcnt vmcnt(3)
	v_lshlrev_b32_e32 v53, 16, v218
	v_mul_f32_e32 v53, 0x3fd744fd, v53
	v_fmac_f32_e32 v53, v48, v217
	s_waitcnt vmcnt(2)
	v_lshlrev_b32_e32 v48, 16, v219
	v_mul_f32_e32 v48, 0x3fd744fd, v48
	v_fmac_f32_e32 v48, v49, v217
	v_cvt_pk_bf16_f32 v48, v48, s0
	ds_write_b16 v61, v48 offset:240
	s_waitcnt vmcnt(1)
	v_lshlrev_b32_e32 v49, 16, v220
	v_mul_f32_e32 v49, 0x3fd744fd, v49
	v_fmac_f32_e32 v49, v50, v217
	v_cvt_pk_bf16_f32 v48, v49, s0
	ds_write_b16 v61, v48 offset:384
	v_add_u32_e32 v49, 0xfffff010, v72
	v_lshrrev_b32_e32 v49, 12, v49
	v_add_u32_e32 v49, 1, v49
	s_waitcnt vmcnt(0)
	v_lshlrev_b32_e32 v50, 16, v221
	v_mul_f32_e32 v50, 0x3fd744fd, v50
	v_fmac_f32_e32 v50, v51, v217
	v_cvt_pk_bf16_f32 v48, v50, s0
	ds_write_b16 v61, v48 offset:528
	v_or_b32_e32 v48, 16, v60
	v_cmp_lt_i32_e32 vcc, s9, v48
	v_cvt_pk_bf16_f32 v51, v53, s0
	ds_write_b16 v61, v51 offset:96
	v_cndmask_b32_e32 v136, 0, v49, vcc
	v_ashrrev_i32_e32 v49, 31, v48
	v_lshl_add_u64 v[50:51], v[136:137], 0, s[0:1]
	v_lshlrev_b64 v[48:49], 12, v[48:49]
	v_mad_u64_u32 v[52:53], s[6:7], v50, s5, v[64:65]
	v_lshl_add_u64 v[54:55], v[62:63], 0, v[48:49]
	global_load_ushort v222, v[54:55], off
	v_mad_i32_i24 v53, v51, s5, v53
	v_lshl_add_u64 v[52:53], v[52:53], 0, v[66:67]
	global_load_dword v223, v[52:53], off
	v_or_b32_e32 v50, 17, v60
	v_ashrrev_i32_e32 v51, 31, v50
	v_lshlrev_b64 v[50:51], 12, v[50:51]
	s_waitcnt vmcnt(1)
	v_lshlrev_b32_e32 v48, 16, v222
	v_mul_f32_e32 v69, 0x3fd744fd, v48
	v_lshl_add_u64 v[48:49], v[62:63], 0, v[50:51]
	global_load_ushort v224, v[48:49], off
	s_waitcnt vmcnt(1)
	v_fmac_f32_e32 v69, v44, v223
	v_lshl_add_u64 v[50:51], v[62:63], 0, v[56:57]
	global_load_ushort v225, v[50:51], off
	s_waitcnt vmcnt(1)
	v_lshlrev_b32_e32 v44, 16, v224
	v_mul_f32_e32 v75, 0x3fd744fd, v44
	v_fmac_f32_e32 v75, v45, v223
	s_waitcnt vmcnt(0)
	v_lshlrev_b32_e32 v44, 16, v225
	v_mul_f32_e32 v56, 0x3fd744fd, v44
	v_lshl_add_u64 v[44:45], v[62:63], 0, v[58:59]
	global_load_ushort v226, v[44:45], off
	global_load_dword v227, v[52:53], off offset:64
	global_load_ushort v228, v[54:55], off offset:32
	global_load_ushort v229, v[48:49], off offset:32
	global_load_ushort v230, v[50:51], off offset:32
	global_load_ushort v231, v[44:45], off offset:32
	global_load_dword v232, v[52:53], off offset:128
	global_load_ushort v233, v[54:55], off offset:64
	global_load_ushort v234, v[48:49], off offset:64
	global_load_ushort v235, v[50:51], off offset:64
	global_load_ushort v236, v[44:45], off offset:64
	global_load_dword v237, v[52:53], off offset:192
	global_load_ushort v238, v[54:55], off offset:96
	global_load_ushort v239, v[48:49], off offset:96
	global_load_ushort v240, v[50:51], off offset:96
	global_load_ushort v241, v[44:45], off offset:96
	v_fmac_f32_e32 v56, v46, v223
	s_waitcnt vmcnt(15)
	v_lshlrev_b32_e32 v46, 16, v226
	v_mul_f32_e32 v46, 0x3fd744fd, v46
	v_fmac_f32_e32 v46, v47, v223
	v_cvt_pk_bf16_f32 v47, v69, s0
	ds_write_b16 v61, v47 offset:2304
	v_cvt_pk_bf16_f32 v47, v75, s0
	ds_write_b16 v61, v47 offset:2448
	v_cvt_pk_bf16_f32 v47, v56, s0
	v_cvt_pk_bf16_f32 v46, v46, s0
	ds_write_b16 v61, v47 offset:2592
	ds_write_b16 v61, v46 offset:2736
	s_waitcnt vmcnt(13)
	v_lshlrev_b32_e32 v47, 16, v228
	v_mul_f32_e32 v47, 0x3fd744fd, v47
	v_fmac_f32_e32 v47, v40, v227
	s_waitcnt vmcnt(12)
	v_lshlrev_b32_e32 v40, 16, v229
	v_mul_f32_e32 v40, 0x3fd744fd, v40
	v_fmac_f32_e32 v40, v41, v227
	v_cvt_pk_bf16_f32 v40, v40, s0
	ds_write_b16 v61, v40 offset:2480
	s_waitcnt vmcnt(11)
	v_lshlrev_b32_e32 v41, 16, v230
	v_mul_f32_e32 v41, 0x3fd744fd, v41
	v_fmac_f32_e32 v41, v42, v227
	v_cvt_pk_bf16_f32 v40, v41, s0
	ds_write_b16 v61, v40 offset:2624
	s_waitcnt vmcnt(10)
	v_lshlrev_b32_e32 v42, 16, v231
	v_mul_f32_e32 v42, 0x3fd744fd, v42
	v_fmac_f32_e32 v42, v43, v227
	v_cvt_pk_bf16_f32 v43, v47, s0
	v_cvt_pk_bf16_f32 v40, v42, s0
	ds_write_b16 v61, v43 offset:2336
	ds_write_b16 v61, v40 offset:2768
	s_waitcnt vmcnt(8)
	v_lshlrev_b32_e32 v41, 16, v233
	v_mul_f32_e32 v41, 0x3fd744fd, v41
	v_fmac_f32_e32 v41, v36, v232
	s_waitcnt vmcnt(7)
	v_lshlrev_b32_e32 v36, 16, v234
	v_mul_f32_e32 v36, 0x3fd744fd, v36
	v_fmac_f32_e32 v36, v37, v232
	v_cvt_pk_bf16_f32 v36, v36, s0
	ds_write_b16 v61, v36 offset:2512
	s_waitcnt vmcnt(6)
	v_lshlrev_b32_e32 v37, 16, v235
	v_mul_f32_e32 v37, 0x3fd744fd, v37
	v_fmac_f32_e32 v37, v38, v232
	v_cvt_pk_bf16_f32 v36, v37, s0
	ds_write_b16 v61, v36 offset:2656
	s_waitcnt vmcnt(5)
	v_lshlrev_b32_e32 v38, 16, v236
	v_mul_f32_e32 v38, 0x3fd744fd, v38
	v_fmac_f32_e32 v38, v39, v232
	v_cvt_pk_bf16_f32 v39, v41, s0
	v_cvt_pk_bf16_f32 v36, v38, s0
	ds_write_b16 v61, v39 offset:2368
	ds_write_b16 v61, v36 offset:2800
	v_or_b32_e32 v38, 34, v60
	v_ashrrev_i32_e32 v39, 31, v38
	v_lshlrev_b64 v[40:41], 12, v[38:39]
	v_or_b32_e32 v38, 35, v60
	v_ashrrev_i32_e32 v39, 31, v38
	v_lshlrev_b64 v[42:43], 12, v[38:39]
	s_waitcnt vmcnt(3)
	v_lshlrev_b32_e32 v37, 16, v238
	v_mul_f32_e32 v37, 0x3fd744fd, v37
	v_fmac_f32_e32 v37, v32, v237
	s_waitcnt vmcnt(2)
	v_lshlrev_b32_e32 v32, 16, v239
	v_mul_f32_e32 v32, 0x3fd744fd, v32
	v_fmac_f32_e32 v32, v33, v237
	v_cvt_pk_bf16_f32 v32, v32, s0
	ds_write_b16 v61, v32 offset:2544
	s_waitcnt vmcnt(1)
	v_lshlrev_b32_e32 v33, 16, v240
	v_mul_f32_e32 v33, 0x3fd744fd, v33
	v_fmac_f32_e32 v33, v34, v237
	v_cvt_pk_bf16_f32 v32, v33, s0
	ds_write_b16 v61, v32 offset:2688
	v_add_u32_e32 v33, 0xfffff020, v72
	v_lshrrev_b32_e32 v33, 12, v33
	v_add_u32_e32 v33, 1, v33
	s_waitcnt vmcnt(0)
	v_lshlrev_b32_e32 v34, 16, v241
	v_mul_f32_e32 v34, 0x3fd744fd, v34
	v_fmac_f32_e32 v34, v35, v237
	v_cvt_pk_bf16_f32 v32, v34, s0
	ds_write_b16 v61, v32 offset:2832
	v_or_b32_e32 v32, 32, v60
	v_cmp_lt_i32_e32 vcc, s9, v32
	v_cvt_pk_bf16_f32 v35, v37, s0
	ds_write_b16 v61, v35 offset:2400
	v_cndmask_b32_e32 v136, 0, v33, vcc
	v_ashrrev_i32_e32 v33, 31, v32
	v_lshl_add_u64 v[34:35], v[136:137], 0, s[0:1]
	v_lshlrev_b64 v[32:33], 12, v[32:33]
	v_mad_u64_u32 v[36:37], s[6:7], v34, s5, v[64:65]
	v_lshl_add_u64 v[38:39], v[62:63], 0, v[32:33]
	global_load_ushort v248, v[38:39], off
	v_mad_i32_i24 v37, v35, s5, v37
	v_lshl_add_u64 v[36:37], v[36:37], 0, v[66:67]
	global_load_dword v249, v[36:37], off
	v_or_b32_e32 v34, 33, v60
	v_ashrrev_i32_e32 v35, 31, v34
	v_lshlrev_b64 v[34:35], 12, v[34:35]
	s_waitcnt vmcnt(1)
	v_lshlrev_b32_e32 v32, 16, v248
	v_mul_f32_e32 v45, 0x3fd744fd, v32
	v_lshl_add_u64 v[32:33], v[62:63], 0, v[34:35]
	global_load_ushort v250, v[32:33], off
	s_waitcnt vmcnt(1)
	v_fmac_f32_e32 v45, v28, v249
	v_lshl_add_u64 v[34:35], v[62:63], 0, v[40:41]
	global_load_ushort v251, v[34:35], off
	s_waitcnt vmcnt(1)
	v_lshlrev_b32_e32 v28, 16, v250
	v_mul_f32_e32 v46, 0x3fd744fd, v28
	v_fmac_f32_e32 v46, v29, v249
	s_waitcnt vmcnt(0)
	v_lshlrev_b32_e32 v28, 16, v251
	v_mul_f32_e32 v40, 0x3fd744fd, v28
	v_lshl_add_u64 v[28:29], v[62:63], 0, v[42:43]
	global_load_ushort v252, v[28:29], off
	global_load_dword v253, v[36:37], off offset:64
	global_load_ushort v254, v[38:39], off offset:32
	global_load_ushort v255, v[32:33], off offset:32
	global_load_ushort v202, v[34:35], off offset:32
	global_load_ushort v203, v[28:29], off offset:32
	global_load_dword v204, v[36:37], off offset:128
	global_load_ushort v205, v[38:39], off offset:64
	global_load_ushort v206, v[32:33], off offset:64
	global_load_ushort v207, v[34:35], off offset:64
	global_load_ushort v208, v[28:29], off offset:64
	global_load_dword v209, v[36:37], off offset:192
	global_load_ushort v210, v[38:39], off offset:96
	global_load_ushort v211, v[32:33], off offset:96
	global_load_ushort v212, v[34:35], off offset:96
	global_load_ushort v213, v[28:29], off offset:96
	v_fmac_f32_e32 v40, v30, v249
	s_waitcnt vmcnt(15)
	v_lshlrev_b32_e32 v30, 16, v252
	v_mul_f32_e32 v30, 0x3fd744fd, v30
	v_fmac_f32_e32 v30, v31, v249
	v_cvt_pk_bf16_f32 v31, v45, s0
	ds_write_b16 v61, v31 offset:4608
	v_cvt_pk_bf16_f32 v31, v46, s0
	ds_write_b16 v61, v31 offset:4752
	v_cvt_pk_bf16_f32 v31, v40, s0
	v_cvt_pk_bf16_f32 v30, v30, s0
	ds_write_b16 v61, v31 offset:4896
	ds_write_b16 v61, v30 offset:5040
	s_waitcnt vmcnt(13)
	v_lshlrev_b32_e32 v31, 16, v254
	v_mul_f32_e32 v31, 0x3fd744fd, v31
	v_fmac_f32_e32 v31, v24, v253
	s_waitcnt vmcnt(12)
	v_lshlrev_b32_e32 v24, 16, v255
	v_mul_f32_e32 v24, 0x3fd744fd, v24
	v_fmac_f32_e32 v24, v25, v253
	v_cvt_pk_bf16_f32 v24, v24, s0
	ds_write_b16 v61, v24 offset:4784
	s_waitcnt vmcnt(11)
	v_lshlrev_b32_e32 v25, 16, v202
	v_mul_f32_e32 v25, 0x3fd744fd, v25
	v_fmac_f32_e32 v25, v26, v253
	v_cvt_pk_bf16_f32 v24, v25, s0
	ds_write_b16 v61, v24 offset:4928
	s_waitcnt vmcnt(10)
	v_lshlrev_b32_e32 v26, 16, v203
	v_mul_f32_e32 v26, 0x3fd744fd, v26
	v_fmac_f32_e32 v26, v27, v253
	v_cvt_pk_bf16_f32 v27, v31, s0
	v_cvt_pk_bf16_f32 v24, v26, s0
	ds_write_b16 v61, v27 offset:4640
	ds_write_b16 v61, v24 offset:5072
	s_waitcnt vmcnt(8)
	v_lshlrev_b32_e32 v25, 16, v205
	v_mul_f32_e32 v25, 0x3fd744fd, v25
	v_fmac_f32_e32 v25, v20, v204
	s_waitcnt vmcnt(7)
	v_lshlrev_b32_e32 v20, 16, v206
	v_mul_f32_e32 v20, 0x3fd744fd, v20
	v_fmac_f32_e32 v20, v21, v204
	v_cvt_pk_bf16_f32 v20, v20, s0
	ds_write_b16 v61, v20 offset:4816
	s_waitcnt vmcnt(6)
	v_lshlrev_b32_e32 v21, 16, v207
	v_mul_f32_e32 v21, 0x3fd744fd, v21
	v_fmac_f32_e32 v21, v22, v204
	v_cvt_pk_bf16_f32 v20, v21, s0
	ds_write_b16 v61, v20 offset:4960
	s_waitcnt vmcnt(5)
	v_lshlrev_b32_e32 v22, 16, v208
	v_mul_f32_e32 v22, 0x3fd744fd, v22
	v_fmac_f32_e32 v22, v23, v204
	v_cvt_pk_bf16_f32 v23, v25, s0
	v_cvt_pk_bf16_f32 v20, v22, s0
	ds_write_b16 v61, v23 offset:4672
	ds_write_b16 v61, v20 offset:5104
	v_or_b32_e32 v22, 50, v60
	v_ashrrev_i32_e32 v23, 31, v22
	v_lshlrev_b64 v[24:25], 12, v[22:23]
	v_or_b32_e32 v22, 51, v60
	v_ashrrev_i32_e32 v23, 31, v22
	v_lshlrev_b64 v[26:27], 12, v[22:23]
	s_waitcnt vmcnt(3)
	v_lshlrev_b32_e32 v21, 16, v210
	v_mul_f32_e32 v21, 0x3fd744fd, v21
	v_fmac_f32_e32 v21, v16, v209
	s_waitcnt vmcnt(2)
	v_lshlrev_b32_e32 v16, 16, v211
	v_mul_f32_e32 v16, 0x3fd744fd, v16
	v_fmac_f32_e32 v16, v17, v209
	v_cvt_pk_bf16_f32 v16, v16, s0
	ds_write_b16 v61, v16 offset:4848
	s_waitcnt vmcnt(1)
	v_lshlrev_b32_e32 v17, 16, v212
	v_mul_f32_e32 v17, 0x3fd744fd, v17
	v_fmac_f32_e32 v17, v18, v209
	v_cvt_pk_bf16_f32 v16, v17, s0
	ds_write_b16 v61, v16 offset:4992
	v_add_u32_e32 v17, 0xfffff030, v72
	v_lshrrev_b32_e32 v17, 12, v17
	v_add_u32_e32 v17, 1, v17
	s_waitcnt vmcnt(0)
	v_lshlrev_b32_e32 v18, 16, v213
	v_mul_f32_e32 v18, 0x3fd744fd, v18
	v_fmac_f32_e32 v18, v19, v209
	v_cvt_pk_bf16_f32 v16, v18, s0
	ds_write_b16 v61, v16 offset:5136
	v_or_b32_e32 v16, 48, v60
	v_cmp_lt_i32_e32 vcc, s9, v16
	v_cvt_pk_bf16_f32 v19, v21, s0
	ds_write_b16 v61, v19 offset:4704
	v_cndmask_b32_e32 v136, 0, v17, vcc
	v_ashrrev_i32_e32 v17, 31, v16
	v_lshl_add_u64 v[18:19], v[136:137], 0, s[0:1]
	v_lshlrev_b64 v[16:17], 12, v[16:17]
	v_mad_u64_u32 v[20:21], s[6:7], v18, s5, v[64:65]
	v_lshl_add_u64 v[22:23], v[62:63], 0, v[16:17]
	global_load_ushort v214, v[22:23], off
	v_mad_i32_i24 v21, v19, s5, v21
	v_lshl_add_u64 v[20:21], v[20:21], 0, v[66:67]
	global_load_dword v215, v[20:21], off
	v_or_b32_e32 v18, 49, v60
	v_ashrrev_i32_e32 v19, 31, v18
	v_lshlrev_b64 v[18:19], 12, v[18:19]
	s_ashr_i32 s5, s4, 31
	s_lshl_b64 s[4:5], s[4:5], 1
	s_add_u32 s4, s46, s4
	s_addc_u32 s5, s47, s5
	v_lshlrev_b32_e32 v136, 1, v73
	s_add_i32 s8, s8, 1
	s_mov_b64 s[6:7], 0
	s_waitcnt vmcnt(1)
	v_lshlrev_b32_e32 v16, 16, v214
	v_mul_f32_e32 v29, 0x3fd744fd, v16
	v_lshl_add_u64 v[16:17], v[62:63], 0, v[18:19]
	global_load_ushort v216, v[16:17], off
	s_waitcnt vmcnt(1)
	v_fmac_f32_e32 v29, v12, v215
	v_lshl_add_u64 v[18:19], v[62:63], 0, v[24:25]
	global_load_ushort v217, v[18:19], off
	s_waitcnt vmcnt(1)
	v_lshlrev_b32_e32 v12, 16, v216
	v_mul_f32_e32 v30, 0x3fd744fd, v12
	v_fmac_f32_e32 v30, v13, v215
	s_waitcnt vmcnt(0)
	v_lshlrev_b32_e32 v12, 16, v217
	v_mul_f32_e32 v24, 0x3fd744fd, v12
	v_lshl_add_u64 v[12:13], v[62:63], 0, v[26:27]
	global_load_ushort v218, v[12:13], off
	global_load_dword v219, v[20:21], off offset:64
	global_load_ushort v220, v[22:23], off offset:32
	global_load_ushort v221, v[16:17], off offset:32
	global_load_ushort v222, v[18:19], off offset:32
	global_load_ushort v223, v[12:13], off offset:32
	global_load_dword v224, v[20:21], off offset:128
	global_load_ushort v225, v[22:23], off offset:64
	global_load_ushort v226, v[16:17], off offset:64
	global_load_ushort v227, v[18:19], off offset:64
	global_load_ushort v228, v[12:13], off offset:64
	global_load_dword v229, v[20:21], off offset:192
	global_load_ushort v230, v[22:23], off offset:96
	global_load_ushort v231, v[16:17], off offset:96
	global_load_ushort v232, v[18:19], off offset:96
	global_load_ushort v233, v[12:13], off offset:96
	v_fmac_f32_e32 v24, v14, v215
	s_waitcnt vmcnt(15)
	v_lshlrev_b32_e32 v14, 16, v218
	v_mul_f32_e32 v14, 0x3fd744fd, v14
	v_fmac_f32_e32 v14, v15, v215
	v_cvt_pk_bf16_f32 v15, v29, s0
	ds_write_b16 v61, v15 offset:6912
	v_cvt_pk_bf16_f32 v15, v30, s0
	ds_write_b16 v61, v15 offset:7056
	v_cvt_pk_bf16_f32 v15, v24, s0
	v_cvt_pk_bf16_f32 v14, v14, s0
	ds_write_b16 v61, v15 offset:7200
	ds_write_b16 v61, v14 offset:7344
	s_waitcnt vmcnt(13)
	v_lshlrev_b32_e32 v15, 16, v220
	v_mul_f32_e32 v15, 0x3fd744fd, v15
	v_fmac_f32_e32 v15, v8, v219
	s_waitcnt vmcnt(12)
	v_lshlrev_b32_e32 v8, 16, v221
	v_mul_f32_e32 v8, 0x3fd744fd, v8
	v_fmac_f32_e32 v8, v9, v219
	v_cvt_pk_bf16_f32 v8, v8, s0
	ds_write_b16 v61, v8 offset:7088
	s_waitcnt vmcnt(11)
	v_lshlrev_b32_e32 v9, 16, v222
	v_mul_f32_e32 v9, 0x3fd744fd, v9
	v_fmac_f32_e32 v9, v10, v219
	v_cvt_pk_bf16_f32 v8, v9, s0
	ds_write_b16 v61, v8 offset:7232
	s_waitcnt vmcnt(10)
	v_lshlrev_b32_e32 v10, 16, v223
	v_mul_f32_e32 v10, 0x3fd744fd, v10
	v_fmac_f32_e32 v10, v11, v219
	v_cvt_pk_bf16_f32 v11, v15, s0
	v_cvt_pk_bf16_f32 v8, v10, s0
	ds_write_b16 v61, v11 offset:6944
	ds_write_b16 v61, v8 offset:7376
	s_waitcnt vmcnt(8)
	v_lshlrev_b32_e32 v9, 16, v225
	v_mul_f32_e32 v9, 0x3fd744fd, v9
	v_fmac_f32_e32 v9, v4, v224
	s_waitcnt vmcnt(7)
	v_lshlrev_b32_e32 v4, 16, v226
	v_mul_f32_e32 v4, 0x3fd744fd, v4
	v_fmac_f32_e32 v4, v5, v224
	v_cvt_pk_bf16_f32 v4, v4, s0
	ds_write_b16 v61, v4 offset:7120
	s_waitcnt vmcnt(6)
	v_lshlrev_b32_e32 v5, 16, v227
	v_mul_f32_e32 v5, 0x3fd744fd, v5
	v_fmac_f32_e32 v5, v6, v224
	v_cvt_pk_bf16_f32 v4, v5, s0
	ds_write_b16 v61, v4 offset:7264
	s_waitcnt vmcnt(5)
	v_lshlrev_b32_e32 v6, 16, v228
	v_mul_f32_e32 v6, 0x3fd744fd, v6
	v_fmac_f32_e32 v6, v7, v224
	v_cvt_pk_bf16_f32 v7, v9, s0
	v_cvt_pk_bf16_f32 v4, v6, s0
	ds_write_b16 v61, v7 offset:6976
	ds_write_b16 v61, v4 offset:7408
	s_waitcnt vmcnt(3)
	v_lshlrev_b32_e32 v5, 16, v230
	v_mul_f32_e32 v5, 0x3fd744fd, v5
	v_fmac_f32_e32 v5, v0, v229
	s_waitcnt vmcnt(2)
	v_lshlrev_b32_e32 v0, 16, v231
	v_mul_f32_e32 v0, 0x3fd744fd, v0
	v_fmac_f32_e32 v0, v1, v229
	v_cvt_pk_bf16_f32 v0, v0, s0
	ds_write_b16 v61, v0 offset:7152
	s_waitcnt vmcnt(1)
	v_lshlrev_b32_e32 v1, 16, v232
	v_mul_f32_e32 v1, 0x3fd744fd, v1
	v_fmac_f32_e32 v1, v2, v229
	v_cvt_pk_bf16_f32 v0, v1, s0
	ds_write_b16 v61, v0 offset:7296
	v_mov_b32_e32 v1, v137
	s_waitcnt vmcnt(0)
	v_lshlrev_b32_e32 v2, 16, v233
	v_mul_f32_e32 v2, 0x3fd744fd, v2
	v_fmac_f32_e32 v2, v3, v229
	v_cvt_pk_bf16_f32 v0, v2, s0
	ds_write_b16 v61, v0 offset:7440
	v_lshlrev_b32_e32 v0, 4, v71
	v_cvt_pk_bf16_f32 v3, v5, s0
	v_and_b32_e32 v0, 0x70, v0
	ds_write_b16 v61, v3 offset:7008
	v_or_b32_e32 v6, v74, v0
	v_lshl_add_u64 v[2:3], s[4:5], 0, v[136:137]
	s_movk_i32 s4, 0x90
	v_mad_u32_u24 v10, v70, s4, v6
	v_lshl_add_u64 v[4:5], v[2:3], 0, v[0:1]
	ds_read_b128 v[0:3], v10
	v_or_b32_e32 v6, v72, v70
	v_ashrrev_i32_e32 v7, 31, v6
	v_lshlrev_b64 v[8:9], 12, v[6:7]
	v_lshl_add_u64 v[8:9], v[4:5], 0, v[8:9]
	s_waitcnt lgkmcnt(0)
	global_store_dwordx4 v[8:9], v[0:3], off offset:2048
	ds_read_b128 v[0:3], v10 offset:1152
	v_or_b32_e32 v8, 8, v6
	v_ashrrev_i32_e32 v9, 31, v8
	v_lshlrev_b64 v[8:9], 12, v[8:9]
	v_lshl_add_u64 v[8:9], v[4:5], 0, v[8:9]
	s_waitcnt lgkmcnt(0)
	global_store_dwordx4 v[8:9], v[0:3], off offset:2048
	ds_read_b128 v[0:3], v10 offset:2304
	v_or_b32_e32 v8, 16, v6
	v_ashrrev_i32_e32 v9, 31, v8
	v_lshlrev_b64 v[8:9], 12, v[8:9]
	v_lshl_add_u64 v[8:9], v[4:5], 0, v[8:9]
	s_waitcnt lgkmcnt(0)
	global_store_dwordx4 v[8:9], v[0:3], off offset:2048
	ds_read_b128 v[0:3], v10 offset:3456
	v_or_b32_e32 v8, 24, v6
	v_ashrrev_i32_e32 v9, 31, v8
	v_lshlrev_b64 v[8:9], 12, v[8:9]
	v_lshl_add_u64 v[8:9], v[4:5], 0, v[8:9]
	s_waitcnt lgkmcnt(0)
	global_store_dwordx4 v[8:9], v[0:3], off offset:2048
	ds_read_b128 v[0:3], v10 offset:4608
	v_or_b32_e32 v8, 32, v6
	v_ashrrev_i32_e32 v9, 31, v8
	v_lshlrev_b64 v[8:9], 12, v[8:9]
	v_lshl_add_u64 v[8:9], v[4:5], 0, v[8:9]
	s_waitcnt lgkmcnt(0)
	global_store_dwordx4 v[8:9], v[0:3], off offset:2048
	ds_read_b128 v[0:3], v10 offset:5760
	v_or_b32_e32 v8, 40, v6
	v_ashrrev_i32_e32 v9, 31, v8
	v_lshlrev_b64 v[8:9], 12, v[8:9]
	v_lshl_add_u64 v[8:9], v[4:5], 0, v[8:9]
	s_waitcnt lgkmcnt(0)
	global_store_dwordx4 v[8:9], v[0:3], off offset:2048
	ds_read_b128 v[0:3], v10 offset:6912
	v_or_b32_e32 v8, 48, v6
	v_ashrrev_i32_e32 v9, 31, v8
	v_lshlrev_b64 v[8:9], 12, v[8:9]
	v_lshl_add_u64 v[8:9], v[4:5], 0, v[8:9]
	s_waitcnt lgkmcnt(0)
	global_store_dwordx4 v[8:9], v[0:3], off offset:2048
	ds_read_b128 v[0:3], v10 offset:8064
	v_or_b32_e32 v6, 56, v6
	v_ashrrev_i32_e32 v7, 31, v6
	v_lshlrev_b64 v[6:7], 12, v[6:7]
	v_lshl_add_u64 v[4:5], v[4:5], 0, v[6:7]
	s_waitcnt lgkmcnt(0)
	global_store_dwordx4 v[4:5], v[0:3], off offset:2048
	s_barrier
	s_branch .LBB0_162

.LBB0_1105:
	v_mov_b32_e32 v69, v139
	v_readlane_b32 s40, v246, 9
	v_ashrrev_i32_e32 v72, 6, v69
	v_lshlrev_b32_e32 v6, 3, v72
	v_bfe_u32 v68, v69, 3, 3
	s_lshl_b32 s1, s7, 7
	s_waitcnt lgkmcnt(0)
	v_or_b32_e32 v2, v6, v68
	v_readlane_b32 s54, v246, 23
	v_readlane_b32 s55, v246, 24
	v_lshrrev_b32_e32 v7, 1, v2
	v_add_u32_e32 v4, s1, v2
	v_readlane_b32 s41, v246, 10
	v_readlane_b32 s42, v246, 11
	v_readlane_b32 s43, v246, 12
	v_readlane_b32 s44, v246, 13
	v_readlane_b32 s45, v246, 14
	v_readlane_b32 s46, v246, 15
	v_readlane_b32 s47, v246, 16
	v_readlane_b32 s48, v246, 17
	v_readlane_b32 s49, v246, 18
	v_readlane_b32 s50, v246, 19
	v_readlane_b32 s51, v246, 20
	v_mov_b64_e32 v[0:1], s[54:55]
	v_xor_b32_e32 v3, v7, v69
	v_mad_i64_i32 v[0:1], s[4:5], v4, s36, v[0:1]
	v_readlane_b32 s36, v247, 57
	s_lshl_b32 s0, s8, 7
	v_lshlrev_b32_e32 v3, 4, v3
	v_readlane_b32 s48, v246, 5
	v_readlane_b32 s49, v246, 6
	v_and_b32_e32 v136, 0x70, v3
	v_add_u32_e32 v4, s0, v2
	s_movk_i32 s9, 0x880
	v_mov_b64_e32 v[2:3], s[48:49]
	v_mad_i64_i32 v[2:3], s[4:5], v4, s9, v[2:3]
	v_lshlrev_b32_e32 v74, 10, v72
	v_add_u32_e32 v4, 0x4000, v74
	v_readfirstlane_b32 s4, v74
	v_lshl_add_u64 v[0:1], v[0:1], 0, v[136:137]
	s_mov_b32 m0, s4
	v_readfirstlane_b32 s4, v4
	v_add_u32_e32 v9, 0x1000, v74
	v_lshl_add_u64 v[2:3], v[2:3], 0, v[136:137]
	global_load_lds_dwordx4 v[0:1], off
	s_mov_b32 m0, s4
	s_mov_b64 s[10:11], 0x11000
	v_readfirstlane_b32 s4, v9
	v_add_u32_e32 v9, 0x5000, v74
	global_load_lds_dwordx4 v[2:3], off
	v_lshl_add_u64 v[4:5], v[0:1], 0, s[10:11]
	s_mov_b32 m0, s4
	v_readfirstlane_b32 s4, v9
	v_add_u32_e32 v9, 0x2000, v74
	global_load_lds_dwordx4 v[4:5], off
	v_lshl_add_u64 v[4:5], v[2:3], 0, s[10:11]
	s_mov_b32 m0, s4
	s_mov_b64 s[10:11], 0x22000
	v_readfirstlane_b32 s4, v9
	v_add_u32_e32 v9, 0x6000, v74
	global_load_lds_dwordx4 v[4:5], off
	v_lshl_add_u64 v[4:5], v[0:1], 0, s[10:11]
	s_mov_b32 m0, s4
	v_readfirstlane_b32 s4, v9
	global_load_lds_dwordx4 v[4:5], off
	v_lshl_add_u64 v[4:5], v[2:3], 0, s[10:11]
	s_mov_b32 m0, s4
	s_mov_b64 s[10:11], 0x33000
	global_load_lds_dwordx4 v[4:5], off
	v_add_u32_e32 v4, 0x3000, v74
	v_lshl_add_u64 v[0:1], v[0:1], 0, s[10:11]
	v_readfirstlane_b32 s4, v4
	s_mov_b32 m0, s4
	v_bfe_u32 v71, v69, 4, 2
	global_load_lds_dwordx4 v[0:1], off
	v_lshl_add_u64 v[0:1], v[2:3], 0, s[10:11]
	v_add_u32_e32 v2, 0x7000, v74
	v_and_b32_e32 v73, 15, v69
	v_readfirstlane_b32 s4, v2
	s_mov_b32 m0, s4
	v_lshrrev_b32_e32 v8, 1, v69
	global_load_lds_dwordx4 v[0:1], off
	v_ashrrev_i32_e32 v1, 1, v69
	v_bfe_u32 v0, v69, 1, 3
	v_and_b32_e32 v70, 0xffffffc0, v1
	v_or_b32_e32 v1, v70, v73
	v_bitop3_b32 v0, v71, v0, 4 bitop3:0x36
	v_lshlrev_b32_e32 v75, 7, v1
	v_bitop3_b32 v1, v71, v8, 7 bitop3:0x78
	v_lshlrev_b32_e32 v78, 4, v0
	v_or_b32_e32 v0, s1, v68
	v_lshlrev_b32_e32 v76, 4, v1
	v_lshlrev_b32_e32 v1, 7, v69
	v_add_u32_e32 v0, v0, v6
	v_bitop3_b32 v2, v7, 7, v69 bitop3:0x48
	v_and_b32_e32 v77, 0x2780, v1
	v_mad_i64_i32 v[0:1], s[4:5], v0, s9, 0
	v_lshlrev_b32_e32 v2, 4, v2
	v_or_b32_e32 v0, v0, v2
	v_lshl_add_u64 v[64:65], s[54:55], 0, v[0:1]
	v_or_b32_e32 v0, s0, v68
	v_add_u32_e32 v0, v0, v6
	v_mad_i64_i32 v[0:1], s[4:5], v0, s9, 0
	s_waitcnt vmcnt(0)
	v_or_b32_e32 v0, v0, v2
	v_lshl_add_u64 v[66:67], s[48:49], 0, v[0:1]
	v_mov_b32_e32 v0, 0
	s_mov_b32 s9, 0
	s_mov_b64 s[4:5], 0
	v_mov_b32_e32 v1, v0
	v_mov_b32_e32 v2, v0
	v_mov_b32_e32 v3, v0
	v_mov_b32_e32 v4, v0
	v_mov_b32_e32 v5, v0
	v_mov_b32_e32 v6, v0
	v_mov_b32_e32 v7, v0
	v_mov_b32_e32 v8, v0
	v_mov_b32_e32 v9, v0
	v_mov_b32_e32 v10, v0
	v_mov_b32_e32 v11, v0
	v_mov_b32_e32 v12, v0
	v_mov_b32_e32 v13, v0
	v_mov_b32_e32 v14, v0
	v_mov_b32_e32 v15, v0
	v_mov_b32_e32 v16, v0
	v_mov_b32_e32 v17, v0
	v_mov_b32_e32 v18, v0
	v_mov_b32_e32 v19, v0
	v_mov_b32_e32 v20, v0
	v_mov_b32_e32 v21, v0
	v_mov_b32_e32 v22, v0
	v_mov_b32_e32 v23, v0
	v_mov_b32_e32 v24, v0
	v_mov_b32_e32 v25, v0
	v_mov_b32_e32 v26, v0
	v_mov_b32_e32 v27, v0
	v_mov_b32_e32 v28, v0
	v_mov_b32_e32 v29, v0
	v_mov_b32_e32 v30, v0
	v_mov_b32_e32 v31, v0
	v_mov_b32_e32 v32, v0
	v_mov_b32_e32 v33, v0
	v_mov_b32_e32 v34, v0
	v_mov_b32_e32 v35, v0
	v_mov_b32_e32 v36, v0
	v_mov_b32_e32 v37, v0
	v_mov_b32_e32 v38, v0
	v_mov_b32_e32 v39, v0
	v_mov_b32_e32 v40, v0
	v_mov_b32_e32 v41, v0
	v_mov_b32_e32 v42, v0
	v_mov_b32_e32 v43, v0
	v_mov_b32_e32 v44, v0
	v_mov_b32_e32 v45, v0
	v_mov_b32_e32 v46, v0
	v_mov_b32_e32 v47, v0
	v_mov_b32_e32 v48, v0
	v_mov_b32_e32 v49, v0
	v_mov_b32_e32 v50, v0
	v_mov_b32_e32 v51, v0
	v_mov_b32_e32 v52, v0
	v_mov_b32_e32 v53, v0
	v_mov_b32_e32 v54, v0
	v_mov_b32_e32 v55, v0
	v_mov_b32_e32 v56, v0
	v_mov_b32_e32 v57, v0
	v_mov_b32_e32 v58, v0
	v_mov_b32_e32 v59, v0
	v_mov_b32_e32 v60, v0
	v_mov_b32_e32 v61, v0
	v_mov_b32_e32 v62, v0
	v_mov_b32_e32 v63, v0
	s_mov_b64 s[12:13], 0x11080
	s_mov_b64 s[14:15], 0x33080
	s_mov_b64 s[16:17], 0x22080
	v_readlane_b32 s52, v246, 21
	v_readlane_b32 s53, v246, 22
	v_readlane_b32 s37, v247, 58
	v_readlane_b32 s38, v247, 59
	v_readlane_b32 s39, v247, 60
	v_readlane_b32 s40, v247, 61
	v_readlane_b32 s41, v247, 62
	v_readlane_b32 s42, v247, 63
	v_readlane_b32 s43, v246, 0
	v_readlane_b32 s44, v246, 1
	v_readlane_b32 s45, v246, 2
	v_readlane_b32 s46, v246, 3
	v_readlane_b32 s47, v246, 4
	v_readlane_b32 s50, v246, 7
	v_readlane_b32 s51, v246, 8
	s_waitcnt vmcnt(0) lgkmcnt(0)
	s_barrier
	s_bitcmp1_b32 s68, 8
	s_cbranch_scc0 gp1106_skip
	s_setprio 1
gp1106_skip:
.LBB0_1106:
	s_and_b32 s10, s9, 0x8000
	s_xor_b32 s11, s10, 0x8000
	v_add_u32_e32 v79, s11, v74
	v_lshl_add_u64 v[80:81], v[64:65], 0, s[4:5]
	v_readfirstlane_b32 s11, v79
	v_lshl_add_u64 v[82:83], v[80:81], 0, s[28:29]
	s_mov_b32 m0, s11
	v_lshl_add_u64 v[84:85], v[66:67], 0, s[4:5]
	global_load_lds_dwordx4 v[82:83], off
	v_add_u32_e32 v82, 0x4000, v79
	v_lshl_add_u64 v[86:87], v[84:85], 0, s[28:29]
	v_readfirstlane_b32 s11, v82
	s_mov_b32 m0, s11
	v_lshl_add_u64 v[82:83], v[80:81], 0, s[12:13]
	global_load_lds_dwordx4 v[86:87], off
	v_add_u32_e32 v86, 0x1000, v79
	s_nop 0
	v_readfirstlane_b32 s11, v86
	v_add_u32_e32 v86, 0x5000, v79
	s_mov_b32 m0, s11
	v_readfirstlane_b32 s11, v86
	v_add_u32_e32 v86, 0x2000, v79
	global_load_lds_dwordx4 v[82:83], off
	v_lshl_add_u64 v[82:83], v[84:85], 0, s[12:13]
	s_mov_b32 m0, s11
	v_readfirstlane_b32 s11, v86
	v_add_u32_e32 v86, 0x6000, v79
	global_load_lds_dwordx4 v[82:83], off
	v_lshl_add_u64 v[82:83], v[80:81], 0, s[16:17]
	s_mov_b32 m0, s11
	v_readfirstlane_b32 s11, v86
	global_load_lds_dwordx4 v[82:83], off
	v_lshl_add_u64 v[82:83], v[84:85], 0, s[16:17]
	s_mov_b32 m0, s11
	v_lshl_add_u64 v[80:81], v[80:81], 0, s[14:15]
	global_load_lds_dwordx4 v[82:83], off
	v_add_u32_e32 v82, 0x3000, v79
	v_add_u32_e32 v79, 0x7000, v79
	v_readfirstlane_b32 s11, v82
	s_mov_b32 m0, s11
	v_readfirstlane_b32 s11, v79
	global_load_lds_dwordx4 v[80:81], off
	v_lshl_add_u64 v[80:81], v[84:85], 0, s[14:15]
	s_mov_b32 m0, s11
	v_or_b32_e32 v79, s10, v76
	global_load_lds_dwordx4 v[80:81], off
	v_add_u32_e32 v100, v79, v75
	v_add_u32_e32 v79, v79, v77
	ds_read_b128 v[80:83], v100
	ds_read_b128 v[84:87], v100 offset:2048
	ds_read_b128 v[88:91], v79 offset:16384
	ds_read_b128 v[92:95], v79 offset:18432
	ds_read_b128 v[96:99], v100 offset:4096
	ds_read_b128 v[100:103], v100 offset:6144
	ds_read_b128 v[104:107], v79 offset:20480
	ds_read_b128 v[108:111], v79 offset:22528
	v_or_b32_e32 v79, s10, v78
	v_add_u32_e32 v132, v79, v75
	v_add_u32_e32 v79, v79, v77
	ds_read_b128 v[112:115], v132
	ds_read_b128 v[116:119], v132 offset:2048
	ds_read_b128 v[120:123], v79 offset:16384
	ds_read_b128 v[124:127], v79 offset:18432
	ds_read_b128 v[128:131], v132 offset:4096
	ds_read_b128 v[132:135], v132 offset:6144
	ds_read_b128 v[146:149], v79 offset:20480
	ds_read_b128 v[150:153], v79 offset:22528
	s_waitcnt lgkmcnt(0)
	v_mfma_f32_16x16x32_bf16 v[60:63], v[80:83], v[88:91], v[60:63]
	v_mfma_f32_16x16x32_bf16 v[56:59], v[80:83], v[92:95], v[56:59]
	v_mfma_f32_16x16x32_bf16 v[52:55], v[80:83], v[104:107], v[52:55]
	v_mfma_f32_16x16x32_bf16 v[48:51], v[80:83], v[108:111], v[48:51]
	v_mfma_f32_16x16x32_bf16 v[44:47], v[84:87], v[88:91], v[44:47]
	v_mfma_f32_16x16x32_bf16 v[40:43], v[84:87], v[92:95], v[40:43]
	v_mfma_f32_16x16x32_bf16 v[36:39], v[84:87], v[104:107], v[36:39]
	v_mfma_f32_16x16x32_bf16 v[32:35], v[84:87], v[108:111], v[32:35]
	v_mfma_f32_16x16x32_bf16 v[28:31], v[96:99], v[88:91], v[28:31]
	v_mfma_f32_16x16x32_bf16 v[24:27], v[96:99], v[92:95], v[24:27]
	v_mfma_f32_16x16x32_bf16 v[20:23], v[96:99], v[104:107], v[20:23]
	v_mfma_f32_16x16x32_bf16 v[16:19], v[96:99], v[108:111], v[16:19]
	v_mfma_f32_16x16x32_bf16 v[12:15], v[100:103], v[88:91], v[12:15]
	v_mfma_f32_16x16x32_bf16 v[8:11], v[100:103], v[92:95], v[8:11]
	v_mfma_f32_16x16x32_bf16 v[4:7], v[100:103], v[104:107], v[4:7]
	v_mfma_f32_16x16x32_bf16 v[0:3], v[100:103], v[108:111], v[0:3]
	v_mfma_f32_16x16x32_bf16 v[60:63], v[112:115], v[120:123], v[60:63]
	v_mfma_f32_16x16x32_bf16 v[56:59], v[112:115], v[124:127], v[56:59]
	v_mfma_f32_16x16x32_bf16 v[52:55], v[112:115], v[146:149], v[52:55]
	v_mfma_f32_16x16x32_bf16 v[48:51], v[112:115], v[150:153], v[48:51]
	v_mfma_f32_16x16x32_bf16 v[44:47], v[116:119], v[120:123], v[44:47]
	v_mfma_f32_16x16x32_bf16 v[40:43], v[116:119], v[124:127], v[40:43]
	v_mfma_f32_16x16x32_bf16 v[36:39], v[116:119], v[146:149], v[36:39]
	v_mfma_f32_16x16x32_bf16 v[32:35], v[116:119], v[150:153], v[32:35]
	v_mfma_f32_16x16x32_bf16 v[28:31], v[128:131], v[120:123], v[28:31]
	v_mfma_f32_16x16x32_bf16 v[24:27], v[128:131], v[124:127], v[24:27]
	v_mfma_f32_16x16x32_bf16 v[20:23], v[128:131], v[146:149], v[20:23]
	v_mfma_f32_16x16x32_bf16 v[16:19], v[128:131], v[150:153], v[16:19]
	v_mfma_f32_16x16x32_bf16 v[12:15], v[132:135], v[120:123], v[12:15]
	v_mfma_f32_16x16x32_bf16 v[8:11], v[132:135], v[124:127], v[8:11]
	v_mfma_f32_16x16x32_bf16 v[4:7], v[132:135], v[146:149], v[4:7]
	v_mfma_f32_16x16x32_bf16 v[0:3], v[132:135], v[150:153], v[0:3]
	s_add_i32 s9, s9, 0x8000
	s_waitcnt vmcnt(0)
	s_add_u32 s4, s4, 0x80
	s_addc_u32 s5, s5, 0
	s_cmpk_lg_i32 s4, 0x780
	s_barrier
	s_cbranch_scc1 .LBB0_1106
	s_setprio 0
	v_add_u32_e32 v74, v78, v77
	v_add_u32_e32 v102, v78, v75
	v_add_u32_e32 v122, v76, v77
	v_add_u32_e32 v130, v76, v75
	ds_read_b128 v[64:67], v74 offset:55296
	ds_read_b128 v[78:81], v74 offset:53248
	ds_read_b128 v[82:85], v102 offset:38912
	ds_read_b128 v[86:89], v102 offset:36864
	ds_read_b128 v[90:93], v74 offset:51200
	ds_read_b128 v[94:97], v74 offset:49152
	ds_read_b128 v[98:101], v102 offset:34816
	ds_read_b128 v[102:105], v102 offset:32768
	ds_read_b128 v[74:77], v122 offset:55296
	ds_read_b128 v[106:109], v122 offset:53248
	ds_read_b128 v[110:113], v130 offset:38912
	ds_read_b128 v[114:117], v130 offset:36864
	ds_read_b128 v[118:121], v122 offset:51200
	ds_read_b128 v[122:125], v122 offset:49152
	ds_read_b128 v[126:129], v130 offset:34816
	ds_read_b128 v[130:133], v130 offset:32768
	v_and_b32_e32 v134, 64, v69
	s_waitcnt lgkmcnt(0)
	v_mfma_f32_16x16x32_bf16 v[60:63], v[130:133], v[122:125], v[60:63]
	v_mfma_f32_16x16x32_bf16 v[56:59], v[130:133], v[118:121], v[56:59]
	v_mfma_f32_16x16x32_bf16 v[52:55], v[130:133], v[106:109], v[52:55]
	v_mfma_f32_16x16x32_bf16 v[48:51], v[130:133], v[74:77], v[48:51]
	v_mfma_f32_16x16x32_bf16 v[44:47], v[126:129], v[122:125], v[44:47]
	v_mfma_f32_16x16x32_bf16 v[40:43], v[126:129], v[118:121], v[40:43]
	v_mfma_f32_16x16x32_bf16 v[36:39], v[126:129], v[106:109], v[36:39]
	v_mfma_f32_16x16x32_bf16 v[32:35], v[126:129], v[74:77], v[32:35]
	v_mfma_f32_16x16x32_bf16 v[28:31], v[114:117], v[122:125], v[28:31]
	v_mfma_f32_16x16x32_bf16 v[24:27], v[114:117], v[118:121], v[24:27]
	v_mfma_f32_16x16x32_bf16 v[20:23], v[114:117], v[106:109], v[20:23]
	v_mfma_f32_16x16x32_bf16 v[16:19], v[114:117], v[74:77], v[16:19]
	v_mfma_f32_16x16x32_bf16 v[12:15], v[110:113], v[122:125], v[12:15]
	v_mfma_f32_16x16x32_bf16 v[8:11], v[110:113], v[118:121], v[8:11]
	v_mfma_f32_16x16x32_bf16 v[4:7], v[110:113], v[106:109], v[4:7]
	v_mfma_f32_16x16x32_bf16 v[0:3], v[110:113], v[74:77], v[0:3]
	v_mfma_f32_16x16x32_bf16 v[60:63], v[102:105], v[94:97], v[60:63]
	v_mfma_f32_16x16x32_bf16 v[56:59], v[102:105], v[90:93], v[56:59]
	v_mfma_f32_16x16x32_bf16 v[52:55], v[102:105], v[78:81], v[52:55]
	v_mfma_f32_16x16x32_bf16 v[48:51], v[102:105], v[64:67], v[48:51]
	v_mfma_f32_16x16x32_bf16 v[44:47], v[98:101], v[94:97], v[44:47]
	v_mfma_f32_16x16x32_bf16 v[40:43], v[98:101], v[90:93], v[40:43]
	v_mfma_f32_16x16x32_bf16 v[36:39], v[98:101], v[78:81], v[36:39]
	v_mfma_f32_16x16x32_bf16 v[32:35], v[98:101], v[64:67], v[32:35]
	v_mfma_f32_16x16x32_bf16 v[28:31], v[86:89], v[94:97], v[28:31]
	v_mfma_f32_16x16x32_bf16 v[24:27], v[86:89], v[90:93], v[24:27]
	v_mfma_f32_16x16x32_bf16 v[20:23], v[86:89], v[78:81], v[20:23]
	v_mfma_f32_16x16x32_bf16 v[16:19], v[86:89], v[64:67], v[16:19]
	v_mfma_f32_16x16x32_bf16 v[12:15], v[82:85], v[94:97], v[12:15]
	v_mfma_f32_16x16x32_bf16 v[8:11], v[82:85], v[90:93], v[8:11]
	v_mfma_f32_16x16x32_bf16 v[4:7], v[82:85], v[78:81], v[4:7]
	v_mfma_f32_16x16x32_bf16 v[0:3], v[82:85], v[64:67], v[0:3]
	s_movk_i32 s4, 0x2400
	v_mul_lo_u32 v64, v72, s4
	v_lshl_or_b32 v65, v73, 1, v64
	s_movk_i32 s4, 0x240
	v_cvt_pk_bf16_f32 v60, v60, s0
	v_mad_u32_u24 v65, v71, s4, v65
	v_cvt_pk_bf16_f32 v56, v56, s0
	v_cvt_pk_bf16_f32 v52, v52, s0
	v_cvt_pk_bf16_f32 v48, v48, s0
	v_cvt_pk_bf16_f32 v44, v44, s0
	v_cvt_pk_bf16_f32 v40, v40, s0
	v_cvt_pk_bf16_f32 v36, v36, s0
	v_cvt_pk_bf16_f32 v32, v32, s0
	v_cvt_pk_bf16_f32 v28, v28, s0
	v_cvt_pk_bf16_f32 v24, v24, s0
	v_cvt_pk_bf16_f32 v20, v20, s0
	v_cvt_pk_bf16_f32 v16, v16, s0
	v_cvt_pk_bf16_f32 v12, v12, s0
	v_cvt_pk_bf16_f32 v8, v8, s0
	v_cvt_pk_bf16_f32 v4, v4, s0
	v_cvt_pk_bf16_f32 v0, v0, s0
	s_waitcnt vmcnt(0)
	s_barrier
	ds_write_b16 v65, v60
	v_cvt_pk_bf16_f32 v60, v61, s0
	ds_write_b16 v65, v56 offset:32
	v_cvt_pk_bf16_f32 v56, v57, s0
	ds_write_b16 v65, v52 offset:64
	v_cvt_pk_bf16_f32 v52, v53, s0
	ds_write_b16 v65, v48 offset:96
	v_cvt_pk_bf16_f32 v48, v49, s0
	ds_write_b16 v65, v44 offset:2304
	v_cvt_pk_bf16_f32 v44, v45, s0
	ds_write_b16 v65, v40 offset:2336
	v_cvt_pk_bf16_f32 v40, v41, s0
	ds_write_b16 v65, v36 offset:2368
	v_cvt_pk_bf16_f32 v36, v37, s0
	ds_write_b16 v65, v32 offset:2400
	v_cvt_pk_bf16_f32 v32, v33, s0
	ds_write_b16 v65, v28 offset:4608
	v_cvt_pk_bf16_f32 v28, v29, s0
	ds_write_b16 v65, v24 offset:4640
	v_cvt_pk_bf16_f32 v24, v25, s0
	ds_write_b16 v65, v20 offset:4672
	v_cvt_pk_bf16_f32 v20, v21, s0
	ds_write_b16 v65, v16 offset:4704
	v_cvt_pk_bf16_f32 v16, v17, s0
	ds_write_b16 v65, v12 offset:6912
	v_cvt_pk_bf16_f32 v12, v13, s0
	ds_write_b16 v65, v8 offset:6944
	v_cvt_pk_bf16_f32 v8, v9, s0
	ds_write_b16 v65, v4 offset:6976
	v_cvt_pk_bf16_f32 v4, v5, s0
	ds_write_b16 v65, v0 offset:7008
	v_cvt_pk_bf16_f32 v0, v1, s0
	ds_write_b16 v65, v60 offset:144
	v_cvt_pk_bf16_f32 v60, v62, s0
	ds_write_b16 v65, v56 offset:176
	v_cvt_pk_bf16_f32 v56, v58, s0
	ds_write_b16 v65, v52 offset:208
	v_cvt_pk_bf16_f32 v52, v54, s0
	ds_write_b16 v65, v48 offset:240
	v_cvt_pk_bf16_f32 v48, v50, s0
	ds_write_b16 v65, v44 offset:2448
	v_cvt_pk_bf16_f32 v44, v46, s0
	ds_write_b16 v65, v40 offset:2480
	v_cvt_pk_bf16_f32 v40, v42, s0
	ds_write_b16 v65, v36 offset:2512
	v_cvt_pk_bf16_f32 v36, v38, s0
	ds_write_b16 v65, v32 offset:2544
	v_cvt_pk_bf16_f32 v32, v34, s0
	ds_write_b16 v65, v28 offset:4752
	v_cvt_pk_bf16_f32 v28, v30, s0
	ds_write_b16 v65, v24 offset:4784
	v_cvt_pk_bf16_f32 v24, v26, s0
	ds_write_b16 v65, v20 offset:4816
	v_cvt_pk_bf16_f32 v20, v22, s0
	ds_write_b16 v65, v16 offset:4848
	v_cvt_pk_bf16_f32 v16, v18, s0
	ds_write_b16 v65, v12 offset:7056
	v_cvt_pk_bf16_f32 v12, v14, s0
	ds_write_b16 v65, v8 offset:7088
	v_cvt_pk_bf16_f32 v8, v10, s0
	ds_write_b16 v65, v4 offset:7120
	v_cvt_pk_bf16_f32 v4, v6, s0
	ds_write_b16 v65, v0 offset:7152
	v_cvt_pk_bf16_f32 v0, v2, s0
	v_add_u32_e32 v5, s1, v70
	s_ashr_i32 s1, s0, 31
	ds_write_b16 v65, v60 offset:288
	v_cvt_pk_bf16_f32 v60, v63, s0
	ds_write_b16 v65, v56 offset:320
	v_cvt_pk_bf16_f32 v56, v59, s0
	ds_write_b16 v65, v52 offset:352
	v_cvt_pk_bf16_f32 v52, v55, s0
	ds_write_b16 v65, v48 offset:384
	v_cvt_pk_bf16_f32 v48, v51, s0
	ds_write_b16 v65, v44 offset:2592
	v_cvt_pk_bf16_f32 v44, v47, s0
	ds_write_b16 v65, v40 offset:2624
	v_cvt_pk_bf16_f32 v40, v43, s0
	ds_write_b16 v65, v36 offset:2656
	v_cvt_pk_bf16_f32 v36, v39, s0
	ds_write_b16 v65, v32 offset:2688
	v_cvt_pk_bf16_f32 v32, v35, s0
	ds_write_b16 v65, v28 offset:4896
	v_cvt_pk_bf16_f32 v28, v31, s0
	ds_write_b16 v65, v24 offset:4928
	v_cvt_pk_bf16_f32 v24, v27, s0
	ds_write_b16 v65, v20 offset:4960
	v_cvt_pk_bf16_f32 v20, v23, s0
	ds_write_b16 v65, v16 offset:4992
	v_cvt_pk_bf16_f32 v16, v19, s0
	ds_write_b16 v65, v12 offset:7200
	v_cvt_pk_bf16_f32 v12, v15, s0
	ds_write_b16 v65, v8 offset:7232
	v_cvt_pk_bf16_f32 v8, v11, s0
	ds_write_b16 v65, v4 offset:7264
	v_cvt_pk_bf16_f32 v4, v7, s0
	ds_write_b16 v65, v0 offset:7296
	v_cvt_pk_bf16_f32 v0, v3, s0
	s_lshl_b64 s[0:1], s[0:1], 1
	v_readlane_b32 s36, v246, 25
	ds_write_b16 v65, v0 offset:7440
	v_lshlrev_b32_e32 v0, 4, v69
	v_readlane_b32 s37, v246, 26
	s_add_u32 s0, s36, s0
	v_and_b32_e32 v0, 0x70, v0
	s_addc_u32 s1, s37, s1
	v_lshlrev_b32_e32 v136, 1, v134
	ds_write_b16 v65, v4 offset:7408
	v_or_b32_e32 v4, v64, v0
	v_lshl_add_u64 v[2:3], s[0:1], 0, v[136:137]
	s_movk_i32 s0, 0x90
	ds_write_b16 v65, v60 offset:432
	ds_write_b16 v65, v56 offset:464
	ds_write_b16 v65, v52 offset:496
	ds_write_b16 v65, v48 offset:528
	ds_write_b16 v65, v44 offset:2736
	ds_write_b16 v65, v40 offset:2768
	ds_write_b16 v65, v36 offset:2800
	ds_write_b16 v65, v32 offset:2832
	ds_write_b16 v65, v28 offset:5040
	ds_write_b16 v65, v24 offset:5072
	ds_write_b16 v65, v20 offset:5104
	ds_write_b16 v65, v16 offset:5136
	ds_write_b16 v65, v12 offset:7344
	ds_write_b16 v65, v8 offset:7376
	v_mov_b32_e32 v1, v137
	v_mad_u32_u24 v12, v68, s0, v4
	v_lshl_add_u64 v[8:9], v[2:3], 0, v[0:1]
	ds_read_b128 v[0:3], v12
	v_or_b32_e32 v13, v5, v68
	ds_read_b128 v[4:7], v12 offset:1152
	s_movk_i32 s4, 0x1a00
	v_mad_i64_i32 v[10:11], s[0:1], v13, s4, v[8:9]
	s_waitcnt lgkmcnt(1)
	global_store_dwordx4 v[10:11], v[0:3], off
	s_add_i32 s6, s6, 1
	s_movk_i32 s36, 0x880
	v_or_b32_e32 v0, 8, v13
	v_mad_i64_i32 v[0:1], s[0:1], v0, s4, v[8:9]
	s_waitcnt lgkmcnt(0)
	global_store_dwordx4 v[0:1], v[4:7], off
	ds_read_b128 v[0:3], v12 offset:2304
	v_readlane_b32 s38, v246, 27
	v_or_b32_e32 v4, 16, v13
	v_mad_i64_i32 v[10:11], s[0:1], v4, s4, v[8:9]
	ds_read_b128 v[4:7], v12 offset:3456
	s_waitcnt lgkmcnt(1)
	global_store_dwordx4 v[10:11], v[0:3], off
	v_readlane_b32 s39, v246, 28
	v_readlane_b32 s40, v246, 29
	v_or_b32_e32 v0, 24, v13
	v_mad_i64_i32 v[0:1], s[0:1], v0, s4, v[8:9]
	s_waitcnt lgkmcnt(0)
	global_store_dwordx4 v[0:1], v[4:7], off
	ds_read_b128 v[0:3], v12 offset:4608
	v_readlane_b32 s41, v246, 30
	v_or_b32_e32 v4, 32, v13
	v_mad_i64_i32 v[10:11], s[0:1], v4, s4, v[8:9]
	ds_read_b128 v[4:7], v12 offset:5760
	s_waitcnt lgkmcnt(1)
	global_store_dwordx4 v[10:11], v[0:3], off
	v_readlane_b32 s42, v246, 31
	v_readlane_b32 s43, v246, 32
	v_or_b32_e32 v0, 40, v13
	v_mad_i64_i32 v[0:1], s[0:1], v0, s4, v[8:9]
	s_waitcnt lgkmcnt(0)
	global_store_dwordx4 v[0:1], v[4:7], off
	ds_read_b128 v[0:3], v12 offset:6912
	v_readlane_b32 s44, v246, 33
	v_or_b32_e32 v4, 48, v13
	v_mad_i64_i32 v[10:11], s[0:1], v4, s4, v[8:9]
	ds_read_b128 v[4:7], v12 offset:8064
	s_waitcnt lgkmcnt(1)
	global_store_dwordx4 v[10:11], v[0:3], off
	v_readlane_b32 s45, v246, 34
	v_readlane_b32 s46, v246, 35
	v_or_b32_e32 v0, 56, v13
	v_mad_i64_i32 v[0:1], s[0:1], v0, s4, v[8:9]
	s_mov_b64 s[0:1], 0
	v_readlane_b32 s47, v246, 36
	v_readlane_b32 s48, v246, 37
	v_readlane_b32 s49, v246, 38
	v_readlane_b32 s50, v246, 39
	v_readlane_b32 s51, v246, 40
	s_waitcnt lgkmcnt(0)
	global_store_dwordx4 v[0:1], v[4:7], off
	s_barrier
	s_branch .LBB0_1095
